# sc1 (write-through) on the out-proj/in-proj/gate-up epilogue stores so the L2 is clean at the grid barriers, on top of v23
# baseline (speedup 1.0000x reference)
.LBB0_228:
	s_nop 0
	v_lshlrev_b32_e32 v130, 5, v200
	v_and_or_b32 v131, v130, s81, v207
	v_lshlrev_b32_e32 v186, 3, v131
	global_load_dwordx4 v[214:217], v186, s[6:7]
	global_load_dwordx4 v[218:221], v186, s[6:7] offset:16
	s_cmp_lt_i32 s84, 8
	v_add_u32_e32 v130, 0x1000, v130
	s_cselect_b64 vcc, -1, 0
	v_and_or_b32 v132, v130, s81, v207
	v_lshl_add_u64 v[130:131], s[6:7], 0, v[186:187]
	v_cndmask_b32_e32 v212, 1.0, v211, vcc
	s_and_b64 s[50:51], vcc, exec
	v_add_co_u32_e32 v134, vcc, s60, v130
	v_lshlrev_b32_e32 v186, 3, v132
	s_nop 0
	v_addc_co_u32_e32 v135, vcc, 0, v131, vcc
	v_lshl_add_u64 v[132:133], v[130:131], 0, s[24:25]
	v_lshl_add_u64 v[136:137], v[130:131], 0, s[26:27]
	global_load_dwordx4 v[154:157], v186, s[6:7] offset:16
	global_load_dwordx4 v[158:161], v186, s[6:7]
	global_load_dwordx4 v[224:227], v[134:135], off offset:-4096
	global_load_dwordx4 v[174:177], v[134:135], off
	global_load_dwordx4 v[228:231], v[132:133], off offset:16
	global_load_dwordx4 v[170:173], v[136:137], off offset:16
	v_lshl_add_u64 v[138:139], v[130:131], 0, s[38:39]
	v_add_co_u32_e32 v130, vcc, s82, v130
	v_lshl_add_u64 v[140:141], s[6:7], 0, v[186:187]
	s_nop 0
	v_addc_co_u32_e32 v131, vcc, 0, v131, vcc
	v_add_co_u32_e32 v134, vcc, s60, v140
	v_lshl_add_u64 v[132:133], v[140:141], 0, s[24:25]
	s_nop 0
	v_addc_co_u32_e32 v135, vcc, 0, v141, vcc
	v_lshl_add_u64 v[136:137], v[140:141], 0, s[26:27]
	v_add_co_u32_e32 v232, vcc, s82, v140
	v_lshl_add_u64 v[204:205], v[140:141], 0, s[38:39]
	s_nop 0
	v_addc_co_u32_e32 v233, vcc, 0, v141, vcc
	global_load_dwordx4 v[166:169], v[130:131], off
	global_load_dwordx4 v[162:165], v[138:139], off offset:16
	global_load_dwordx4 v[150:153], v[134:135], off offset:-4096
	global_load_dwordx4 v[142:145], v[134:135], off
	global_load_dwordx4 v[146:149], v[132:133], off offset:16
	s_nop 0
	global_load_dwordx4 v[138:141], v[136:137], off offset:16
	s_nop 0
	global_load_dwordx4 v[134:137], v[232:233], off
	global_load_dwordx4 v[130:133], v[204:205], off offset:16
	s_mov_b32 s0, 0x1c600000
	s_cselect_b32 s0, s0, 0x1e600000
	s_add_u32 s0, s74, s0
	s_addc_u32 s41, s75, 0
	s_lshl_b32 s43, s84, 9
	s_and_b32 s43, s43, 0xe00
	s_add_u32 s0, s0, s43
	s_addc_u32 s41, s41, 0
	s_lshl_b32 s43, s61, 1
	s_add_u32 s50, s0, s43
	v_lshlrev_b32_e32 v186, 1, v188
	s_addc_u32 s51, s41, 0
	v_lshl_add_u64 v[204:205], s[50:51], 0, v[186:187]
	v_ashrrev_i32_e32 v201, 31, v200
	v_lshlrev_b64 v[202:203], 12, v[200:201]
	v_lshl_add_u64 v[202:203], v[204:205], 0, v[202:203]
	s_waitcnt vmcnt(0)
	v_pk_mul_f32 v[232:233], v[128:129], v[216:217]
	v_pk_mul_f32 v[234:235], v[126:127], v[214:215]
	v_pk_mul_f32 v[126:127], v[126:127], v[214:215] op_sel:[1,0] op_sel_hi:[0,1]
	v_pk_mul_f32 v[128:129], v[128:129], v[216:217] op_sel:[1,0] op_sel_hi:[0,1]
	v_pk_mul_f32 v[238:239], v[122:123], v[218:219]
	v_pk_mul_f32 v[122:123], v[122:123], v[218:219] op_sel:[1,0] op_sel_hi:[0,1]
	v_add_f32_e32 v126, v126, v127
	v_sub_f32_e32 v127, v232, v233
	v_add_f32_e32 v128, v128, v129
	v_add_f32_e32 v122, v122, v123
	v_pk_mul_f32 v[236:237], v[124:125], v[220:221]
	v_sub_f32_e32 v186, v234, v235
	v_sub_f32_e32 v129, v238, v239
	v_mul_f32_e32 v126, v212, v126
	v_mul_f32_e32 v127, v212, v127
	v_mul_f32_e32 v128, v212, v128
	v_mul_f32_e32 v122, v212, v122
	v_mul_f32_e32 v123, v212, v186
	v_mul_f32_e32 v129, v212, v129
	v_cvt_pk_bf16_f32 v126, v123, v126
	v_cvt_pk_bf16_f32 v127, v127, v128
	v_cvt_pk_bf16_f32 v128, v129, v122
	v_sub_f32_e32 v122, v236, v237
	v_mul_f32_e32 v129, v212, v122
	v_pk_mul_f32 v[122:123], v[124:125], v[220:221] op_sel:[1,0] op_sel_hi:[0,1]
	v_add_f32_e32 v122, v122, v123
	v_mul_f32_e32 v122, v212, v122
	v_cvt_pk_bf16_f32 v129, v129, v122
	v_pk_mul_f32 v[122:123], v[120:121], v[216:217]
	v_pk_mul_f32 v[124:125], v[118:119], v[214:215]
	v_pk_mul_f32 v[118:119], v[118:119], v[214:215] op_sel:[1,0] op_sel_hi:[0,1]
	v_pk_mul_f32 v[120:121], v[120:121], v[216:217] op_sel:[1,0] op_sel_hi:[0,1]
	v_add_f32_e32 v118, v118, v119
	v_sub_f32_e32 v119, v122, v123
	v_add_f32_e32 v120, v120, v121
	v_sub_f32_e32 v124, v124, v125
	v_mul_f32_e32 v118, v212, v118
	v_mul_f32_e32 v119, v212, v119
	v_mul_f32_e32 v120, v212, v120
	global_store_dwordx4 v[202:203], v[126:129], off sc1
	v_mul_f32_e32 v124, v212, v124
	v_cvt_pk_bf16_f32 v118, v124, v118
	v_cvt_pk_bf16_f32 v119, v119, v120
	v_pk_mul_f32 v[120:121], v[114:115], v[218:219]
	v_pk_mul_f32 v[114:115], v[114:115], v[218:219] op_sel:[1,0] op_sel_hi:[0,1]
	v_sub_f32_e32 v120, v120, v121
	v_add_f32_e32 v114, v114, v115
	v_pk_mul_f32 v[122:123], v[116:117], v[220:221]
	v_mul_f32_e32 v120, v212, v120
	v_mul_f32_e32 v114, v212, v114
	v_cvt_pk_bf16_f32 v120, v120, v114
	v_sub_f32_e32 v114, v122, v123
	v_mul_f32_e32 v121, v212, v114
	v_pk_mul_f32 v[114:115], v[116:117], v[220:221] op_sel:[1,0] op_sel_hi:[0,1]
	v_add_f32_e32 v114, v114, v115
	v_mul_f32_e32 v114, v212, v114
	v_cvt_pk_bf16_f32 v121, v121, v114
	global_store_dwordx4 v[202:203], v[118:121], off offset:256 sc1
	v_pk_mul_f32 v[116:117], v[112:113], v[226:227]
	v_pk_mul_f32 v[112:113], v[112:113], v[226:227] op_sel:[1,0] op_sel_hi:[0,1]
	v_pk_mul_f32 v[118:119], v[110:111], v[224:225]
	v_pk_mul_f32 v[110:111], v[110:111], v[224:225] op_sel:[1,0] op_sel_hi:[0,1]
	v_add_f32_e32 v110, v110, v111
	v_sub_f32_e32 v111, v116, v117
	v_add_f32_e32 v112, v112, v113
	v_sub_f32_e32 v118, v118, v119
	v_mul_f32_e32 v110, v212, v110
	v_mul_f32_e32 v111, v212, v111
	v_mul_f32_e32 v112, v212, v112
	v_mul_f32_e32 v118, v212, v118
	v_cvt_pk_bf16_f32 v110, v118, v110
	v_cvt_pk_bf16_f32 v111, v111, v112
	v_pk_mul_f32 v[112:113], v[106:107], v[228:229]
	v_pk_mul_f32 v[106:107], v[106:107], v[228:229] op_sel:[1,0] op_sel_hi:[0,1]
	v_sub_f32_e32 v112, v112, v113
	v_add_f32_e32 v106, v106, v107
	v_pk_mul_f32 v[116:117], v[108:109], v[230:231]
	v_mul_f32_e32 v112, v212, v112
	v_mul_f32_e32 v106, v212, v106
	v_cvt_pk_bf16_f32 v112, v112, v106
	v_sub_f32_e32 v106, v116, v117
	v_mul_f32_e32 v113, v212, v106
	v_pk_mul_f32 v[106:107], v[108:109], v[230:231] op_sel:[1,0] op_sel_hi:[0,1]
	v_add_f32_e32 v106, v106, v107
	v_or_b32_e32 v114, 16, v200
	v_mul_f32_e32 v106, v212, v106
	v_ashrrev_i32_e32 v115, 31, v114
	v_cvt_pk_bf16_f32 v113, v113, v106
	v_pk_mul_f32 v[106:107], v[104:105], v[226:227]
	v_pk_mul_f32 v[108:109], v[102:103], v[224:225]
	v_pk_mul_f32 v[102:103], v[102:103], v[224:225] op_sel:[1,0] op_sel_hi:[0,1]
	v_pk_mul_f32 v[104:105], v[104:105], v[226:227] op_sel:[1,0] op_sel_hi:[0,1]
	v_lshlrev_b64 v[114:115], 12, v[114:115]
	v_add_f32_e32 v102, v102, v103
	v_sub_f32_e32 v103, v106, v107
	v_add_f32_e32 v104, v104, v105
	v_lshl_add_u64 v[114:115], v[204:205], 0, v[114:115]
	v_sub_f32_e32 v108, v108, v109
	v_mul_f32_e32 v102, v212, v102
	v_mul_f32_e32 v103, v212, v103
	v_mul_f32_e32 v104, v212, v104
	global_store_dwordx4 v[114:115], v[110:113], off sc1
	v_mul_f32_e32 v108, v212, v108
	v_cvt_pk_bf16_f32 v102, v108, v102
	v_cvt_pk_bf16_f32 v103, v103, v104
	v_pk_mul_f32 v[104:105], v[98:99], v[228:229]
	v_pk_mul_f32 v[98:99], v[98:99], v[228:229] op_sel:[1,0] op_sel_hi:[0,1]
	v_sub_f32_e32 v104, v104, v105
	v_add_f32_e32 v98, v98, v99
	v_pk_mul_f32 v[106:107], v[100:101], v[230:231]
	v_mul_f32_e32 v104, v212, v104
	v_mul_f32_e32 v98, v212, v98
	v_cvt_pk_bf16_f32 v104, v104, v98
	v_sub_f32_e32 v98, v106, v107
	v_mul_f32_e32 v105, v212, v98
	v_pk_mul_f32 v[98:99], v[100:101], v[230:231] op_sel:[1,0] op_sel_hi:[0,1]
	v_add_f32_e32 v98, v98, v99
	v_mul_f32_e32 v98, v212, v98
	v_cvt_pk_bf16_f32 v105, v105, v98
	global_store_dwordx4 v[114:115], v[102:105], off offset:256 sc1
	v_pk_mul_f32 v[100:101], v[96:97], v[176:177]
	v_pk_mul_f32 v[96:97], v[96:97], v[176:177] op_sel:[1,0] op_sel_hi:[0,1]
	v_pk_mul_f32 v[102:103], v[94:95], v[174:175]
	v_pk_mul_f32 v[94:95], v[94:95], v[174:175] op_sel:[1,0] op_sel_hi:[0,1]
	v_add_f32_e32 v94, v94, v95
	v_sub_f32_e32 v95, v100, v101
	v_add_f32_e32 v96, v96, v97
	v_sub_f32_e32 v102, v102, v103
	v_mul_f32_e32 v94, v212, v94
	v_mul_f32_e32 v95, v212, v95
	v_mul_f32_e32 v96, v212, v96
	v_mul_f32_e32 v102, v212, v102
	v_cvt_pk_bf16_f32 v94, v102, v94
	v_cvt_pk_bf16_f32 v95, v95, v96
	v_pk_mul_f32 v[96:97], v[90:91], v[170:171]
	v_pk_mul_f32 v[90:91], v[90:91], v[170:171] op_sel:[1,0] op_sel_hi:[0,1]
	v_sub_f32_e32 v96, v96, v97
	v_add_f32_e32 v90, v90, v91
	v_pk_mul_f32 v[100:101], v[92:93], v[172:173]
	v_mul_f32_e32 v96, v212, v96
	v_mul_f32_e32 v90, v212, v90
	v_cvt_pk_bf16_f32 v96, v96, v90
	v_sub_f32_e32 v90, v100, v101
	v_mul_f32_e32 v97, v212, v90
	v_pk_mul_f32 v[90:91], v[92:93], v[172:173] op_sel:[1,0] op_sel_hi:[0,1]
	v_add_f32_e32 v90, v90, v91
	v_or_b32_e32 v98, 32, v200
	v_mul_f32_e32 v90, v212, v90
	v_ashrrev_i32_e32 v99, 31, v98
	v_cvt_pk_bf16_f32 v97, v97, v90
	v_pk_mul_f32 v[90:91], v[88:89], v[176:177]
	v_pk_mul_f32 v[92:93], v[86:87], v[174:175]
	v_pk_mul_f32 v[86:87], v[86:87], v[174:175] op_sel:[1,0] op_sel_hi:[0,1]
	v_pk_mul_f32 v[88:89], v[88:89], v[176:177] op_sel:[1,0] op_sel_hi:[0,1]
	v_lshlrev_b64 v[98:99], 12, v[98:99]
	v_add_f32_e32 v86, v86, v87
	v_sub_f32_e32 v87, v90, v91
	v_add_f32_e32 v88, v88, v89
	v_lshl_add_u64 v[98:99], v[204:205], 0, v[98:99]
	v_sub_f32_e32 v92, v92, v93
	v_mul_f32_e32 v86, v212, v86
	v_mul_f32_e32 v87, v212, v87
	v_mul_f32_e32 v88, v212, v88
	global_store_dwordx4 v[98:99], v[94:97], off sc1
	v_mul_f32_e32 v92, v212, v92
	v_cvt_pk_bf16_f32 v86, v92, v86
	v_cvt_pk_bf16_f32 v87, v87, v88
	v_pk_mul_f32 v[88:89], v[82:83], v[170:171]
	v_pk_mul_f32 v[82:83], v[82:83], v[170:171] op_sel:[1,0] op_sel_hi:[0,1]
	v_sub_f32_e32 v88, v88, v89
	v_add_f32_e32 v82, v82, v83
	v_pk_mul_f32 v[90:91], v[84:85], v[172:173]
	v_mul_f32_e32 v88, v212, v88
	v_mul_f32_e32 v82, v212, v82
	v_cvt_pk_bf16_f32 v88, v88, v82
	v_sub_f32_e32 v82, v90, v91
	v_mul_f32_e32 v89, v212, v82
	v_pk_mul_f32 v[82:83], v[84:85], v[172:173] op_sel:[1,0] op_sel_hi:[0,1]
	v_add_f32_e32 v82, v82, v83
	v_mul_f32_e32 v82, v212, v82
	v_cvt_pk_bf16_f32 v89, v89, v82
	global_store_dwordx4 v[98:99], v[86:89], off offset:256 sc1
	v_pk_mul_f32 v[84:85], v[80:81], v[168:169]
	v_pk_mul_f32 v[80:81], v[80:81], v[168:169] op_sel:[1,0] op_sel_hi:[0,1]
	v_pk_mul_f32 v[86:87], v[78:79], v[166:167]
	v_pk_mul_f32 v[78:79], v[78:79], v[166:167] op_sel:[1,0] op_sel_hi:[0,1]
	v_add_f32_e32 v78, v78, v79
	v_sub_f32_e32 v79, v84, v85
	v_add_f32_e32 v80, v80, v81
	v_sub_f32_e32 v86, v86, v87
	v_mul_f32_e32 v78, v212, v78
	v_mul_f32_e32 v79, v212, v79
	v_mul_f32_e32 v80, v212, v80
	v_mul_f32_e32 v86, v212, v86
	v_cvt_pk_bf16_f32 v78, v86, v78
	v_cvt_pk_bf16_f32 v79, v79, v80
	v_pk_mul_f32 v[80:81], v[74:75], v[162:163]
	v_pk_mul_f32 v[74:75], v[74:75], v[162:163] op_sel:[1,0] op_sel_hi:[0,1]
	v_sub_f32_e32 v80, v80, v81
	v_add_f32_e32 v74, v74, v75
	v_pk_mul_f32 v[84:85], v[76:77], v[164:165]
	v_mul_f32_e32 v80, v212, v80
	v_mul_f32_e32 v74, v212, v74
	v_cvt_pk_bf16_f32 v80, v80, v74
	v_sub_f32_e32 v74, v84, v85
	v_mul_f32_e32 v81, v212, v74
	v_pk_mul_f32 v[74:75], v[76:77], v[164:165] op_sel:[1,0] op_sel_hi:[0,1]
	v_add_f32_e32 v74, v74, v75
	v_or_b32_e32 v82, 48, v200
	v_mul_f32_e32 v74, v212, v74
	v_ashrrev_i32_e32 v83, 31, v82
	v_cvt_pk_bf16_f32 v81, v81, v74
	v_pk_mul_f32 v[74:75], v[72:73], v[168:169]
	v_pk_mul_f32 v[76:77], v[70:71], v[166:167]
	v_pk_mul_f32 v[70:71], v[70:71], v[166:167] op_sel:[1,0] op_sel_hi:[0,1]
	v_pk_mul_f32 v[72:73], v[72:73], v[168:169] op_sel:[1,0] op_sel_hi:[0,1]
	v_lshlrev_b64 v[82:83], 12, v[82:83]
	v_add_f32_e32 v70, v70, v71
	v_sub_f32_e32 v71, v74, v75
	v_add_f32_e32 v72, v72, v73
	v_lshl_add_u64 v[82:83], v[204:205], 0, v[82:83]
	v_sub_f32_e32 v76, v76, v77
	v_mul_f32_e32 v70, v212, v70
	v_mul_f32_e32 v71, v212, v71
	v_mul_f32_e32 v72, v212, v72
	global_store_dwordx4 v[82:83], v[78:81], off sc1
	v_mul_f32_e32 v76, v212, v76
	v_cvt_pk_bf16_f32 v70, v76, v70
	v_cvt_pk_bf16_f32 v71, v71, v72
	v_pk_mul_f32 v[72:73], v[66:67], v[162:163]
	v_pk_mul_f32 v[66:67], v[66:67], v[162:163] op_sel:[1,0] op_sel_hi:[0,1]
	v_sub_f32_e32 v72, v72, v73
	v_add_f32_e32 v66, v66, v67
	v_pk_mul_f32 v[74:75], v[68:69], v[164:165]
	v_mul_f32_e32 v72, v212, v72
	v_mul_f32_e32 v66, v212, v66
	v_cvt_pk_bf16_f32 v72, v72, v66
	v_sub_f32_e32 v66, v74, v75
	v_mul_f32_e32 v73, v212, v66
	v_pk_mul_f32 v[66:67], v[68:69], v[164:165] op_sel:[1,0] op_sel_hi:[0,1]
	v_add_f32_e32 v66, v66, v67
	v_mul_f32_e32 v66, v212, v66
	v_cvt_pk_bf16_f32 v73, v73, v66
	global_store_dwordx4 v[82:83], v[70:73], off offset:256 sc1
	v_pk_mul_f32 v[68:69], v[64:65], v[160:161]
	v_pk_mul_f32 v[64:65], v[64:65], v[160:161] op_sel:[1,0] op_sel_hi:[0,1]
	v_pk_mul_f32 v[70:71], v[62:63], v[158:159]
	v_pk_mul_f32 v[62:63], v[62:63], v[158:159] op_sel:[1,0] op_sel_hi:[0,1]
	v_add_f32_e32 v62, v62, v63
	v_sub_f32_e32 v63, v68, v69
	v_add_f32_e32 v64, v64, v65
	v_sub_f32_e32 v70, v70, v71
	v_mul_f32_e32 v62, v212, v62
	v_mul_f32_e32 v63, v212, v63
	v_mul_f32_e32 v64, v212, v64
	v_mul_f32_e32 v70, v212, v70
	v_cvt_pk_bf16_f32 v62, v70, v62
	v_cvt_pk_bf16_f32 v63, v63, v64
	v_pk_mul_f32 v[64:65], v[58:59], v[154:155]
	v_pk_mul_f32 v[58:59], v[58:59], v[154:155] op_sel:[1,0] op_sel_hi:[0,1]
	v_sub_f32_e32 v64, v64, v65
	v_add_f32_e32 v58, v58, v59
	v_pk_mul_f32 v[68:69], v[60:61], v[156:157]
	v_mul_f32_e32 v64, v212, v64
	v_mul_f32_e32 v58, v212, v58
	v_cvt_pk_bf16_f32 v64, v64, v58
	v_sub_f32_e32 v58, v68, v69
	v_mul_f32_e32 v65, v212, v58
	v_pk_mul_f32 v[58:59], v[60:61], v[156:157] op_sel:[1,0] op_sel_hi:[0,1]
	v_add_f32_e32 v58, v58, v59
	v_mul_f32_e32 v58, v212, v58
	v_cvt_pk_bf16_f32 v65, v65, v58
	v_add_co_u32_e32 v58, vcc, s67, v202
	v_pk_mul_f32 v[60:61], v[54:55], v[158:159]
	s_nop 0
	v_addc_co_u32_e32 v59, vcc, 0, v203, vcc
	global_store_dwordx4 v[58:59], v[62:65], off sc1
	v_pk_mul_f32 v[58:59], v[56:57], v[160:161]
	v_pk_mul_f32 v[54:55], v[54:55], v[158:159] op_sel:[1,0] op_sel_hi:[0,1]
	v_pk_mul_f32 v[56:57], v[56:57], v[160:161] op_sel:[1,0] op_sel_hi:[0,1]
	v_add_f32_e32 v54, v54, v55
	v_sub_f32_e32 v55, v58, v59
	v_add_f32_e32 v56, v56, v57
	v_sub_f32_e32 v60, v60, v61
	v_mul_f32_e32 v54, v212, v54
	v_mul_f32_e32 v55, v212, v55
	v_mul_f32_e32 v56, v212, v56
	v_mul_f32_e32 v60, v212, v60
	v_cvt_pk_bf16_f32 v54, v60, v54
	v_cvt_pk_bf16_f32 v55, v55, v56
	v_pk_mul_f32 v[56:57], v[46:47], v[154:155]
	v_pk_mul_f32 v[46:47], v[46:47], v[154:155] op_sel:[1,0] op_sel_hi:[0,1]
	v_sub_f32_e32 v56, v56, v57
	v_add_f32_e32 v46, v46, v47
	v_pk_mul_f32 v[58:59], v[48:49], v[156:157]
	v_mul_f32_e32 v56, v212, v56
	v_mul_f32_e32 v46, v212, v46
	v_cvt_pk_bf16_f32 v56, v56, v46
	v_sub_f32_e32 v46, v58, v59
	v_mul_f32_e32 v57, v212, v46
	v_pk_mul_f32 v[46:47], v[48:49], v[156:157] op_sel:[1,0] op_sel_hi:[0,1]
	v_add_f32_e32 v46, v46, v47
	v_mul_f32_e32 v46, v212, v46
	v_cvt_pk_bf16_f32 v57, v57, v46
	v_pk_mul_f32 v[46:47], v[50:51], v[150:151]
	v_lshl_add_u64 v[66:67], v[202:203], 0, s[16:17]
	v_sub_f32_e32 v46, v46, v47
	global_store_dwordx4 v[66:67], v[54:57], off offset:256 sc1
	v_pk_mul_f32 v[48:49], v[52:53], v[152:153]
	s_nop 0
	v_mul_f32_e32 v56, v212, v46
	v_pk_mul_f32 v[46:47], v[50:51], v[150:151] op_sel:[1,0] op_sel_hi:[0,1]
	v_add_f32_e32 v46, v46, v47
	v_sub_f32_e32 v47, v48, v49
	v_pk_mul_f32 v[48:49], v[52:53], v[152:153] op_sel:[1,0] op_sel_hi:[0,1]
	v_add_f32_e32 v48, v48, v49
	v_mul_f32_e32 v46, v212, v46
	v_mul_f32_e32 v47, v212, v47
	v_mul_f32_e32 v48, v212, v48
	v_cvt_pk_bf16_f32 v46, v56, v46
	v_cvt_pk_bf16_f32 v47, v47, v48
	v_pk_mul_f32 v[48:49], v[42:43], v[146:147]
	v_pk_mul_f32 v[42:43], v[42:43], v[146:147] op_sel:[1,0] op_sel_hi:[0,1]
	v_sub_f32_e32 v48, v48, v49
	v_add_f32_e32 v42, v42, v43
	v_pk_mul_f32 v[50:51], v[44:45], v[148:149]
	v_mul_f32_e32 v48, v212, v48
	v_mul_f32_e32 v42, v212, v42
	v_cvt_pk_bf16_f32 v48, v48, v42
	v_sub_f32_e32 v42, v50, v51
	v_mul_f32_e32 v49, v212, v42
	v_pk_mul_f32 v[42:43], v[44:45], v[148:149] op_sel:[1,0] op_sel_hi:[0,1]
	v_add_f32_e32 v42, v42, v43
	v_mul_f32_e32 v42, v212, v42
	v_cvt_pk_bf16_f32 v49, v49, v42
	v_add_co_u32_e32 v42, vcc, s77, v202
	v_pk_mul_f32 v[44:45], v[38:39], v[150:151]
	s_nop 0
	v_addc_co_u32_e32 v43, vcc, 0, v203, vcc
	global_store_dwordx4 v[42:43], v[46:49], off sc1
	v_pk_mul_f32 v[42:43], v[40:41], v[152:153]
	v_pk_mul_f32 v[38:39], v[38:39], v[150:151] op_sel:[1,0] op_sel_hi:[0,1]
	v_pk_mul_f32 v[40:41], v[40:41], v[152:153] op_sel:[1,0] op_sel_hi:[0,1]
	v_add_f32_e32 v38, v38, v39
	v_sub_f32_e32 v39, v42, v43
	v_add_f32_e32 v40, v40, v41
	v_sub_f32_e32 v44, v44, v45
	v_mul_f32_e32 v38, v212, v38
	v_mul_f32_e32 v39, v212, v39
	v_mul_f32_e32 v40, v212, v40
	v_mul_f32_e32 v44, v212, v44
	v_cvt_pk_bf16_f32 v38, v44, v38
	v_cvt_pk_bf16_f32 v39, v39, v40
	v_pk_mul_f32 v[40:41], v[30:31], v[146:147]
	v_pk_mul_f32 v[30:31], v[30:31], v[146:147] op_sel:[1,0] op_sel_hi:[0,1]
	v_sub_f32_e32 v40, v40, v41
	v_add_f32_e32 v30, v30, v31
	v_pk_mul_f32 v[42:43], v[32:33], v[148:149]
	v_mul_f32_e32 v40, v212, v40
	v_mul_f32_e32 v30, v212, v30
	v_cvt_pk_bf16_f32 v40, v40, v30
	v_sub_f32_e32 v30, v42, v43
	v_mul_f32_e32 v41, v212, v30
	v_pk_mul_f32 v[30:31], v[32:33], v[148:149] op_sel:[1,0] op_sel_hi:[0,1]
	v_add_f32_e32 v30, v30, v31
	v_mul_f32_e32 v30, v212, v30
	v_cvt_pk_bf16_f32 v41, v41, v30
	v_pk_mul_f32 v[30:31], v[34:35], v[142:143]
	v_lshl_add_u64 v[54:55], v[202:203], 0, s[20:21]
	v_sub_f32_e32 v30, v30, v31
	global_store_dwordx4 v[54:55], v[38:41], off offset:256 sc1
	v_pk_mul_f32 v[32:33], v[36:37], v[144:145]
	s_nop 0
	v_mul_f32_e32 v40, v212, v30
	v_pk_mul_f32 v[30:31], v[34:35], v[142:143] op_sel:[1,0] op_sel_hi:[0,1]
	v_add_f32_e32 v30, v30, v31
	v_sub_f32_e32 v31, v32, v33
	v_pk_mul_f32 v[32:33], v[36:37], v[144:145] op_sel:[1,0] op_sel_hi:[0,1]
	v_add_f32_e32 v32, v32, v33
	v_mul_f32_e32 v30, v212, v30
	v_mul_f32_e32 v31, v212, v31
	v_mul_f32_e32 v32, v212, v32
	v_cvt_pk_bf16_f32 v30, v40, v30
	v_cvt_pk_bf16_f32 v31, v31, v32
	v_pk_mul_f32 v[32:33], v[26:27], v[138:139]
	v_pk_mul_f32 v[26:27], v[26:27], v[138:139] op_sel:[1,0] op_sel_hi:[0,1]
	v_sub_f32_e32 v32, v32, v33
	v_add_f32_e32 v26, v26, v27
	v_pk_mul_f32 v[34:35], v[28:29], v[140:141]
	v_mul_f32_e32 v32, v212, v32
	v_mul_f32_e32 v26, v212, v26
	v_cvt_pk_bf16_f32 v32, v32, v26
	v_sub_f32_e32 v26, v34, v35
	v_mul_f32_e32 v33, v212, v26
	v_pk_mul_f32 v[26:27], v[28:29], v[140:141] op_sel:[1,0] op_sel_hi:[0,1]
	v_add_f32_e32 v26, v26, v27
	v_mul_f32_e32 v26, v212, v26
	v_cvt_pk_bf16_f32 v33, v33, v26
	v_add_co_u32_e32 v26, vcc, s76, v202
	v_pk_mul_f32 v[28:29], v[22:23], v[142:143]
	s_nop 0
	v_addc_co_u32_e32 v27, vcc, 0, v203, vcc
	global_store_dwordx4 v[26:27], v[30:33], off sc1
	v_pk_mul_f32 v[26:27], v[24:25], v[144:145]
	v_pk_mul_f32 v[22:23], v[22:23], v[142:143] op_sel:[1,0] op_sel_hi:[0,1]
	v_pk_mul_f32 v[24:25], v[24:25], v[144:145] op_sel:[1,0] op_sel_hi:[0,1]
	v_add_f32_e32 v22, v22, v23
	v_sub_f32_e32 v23, v26, v27
	v_add_f32_e32 v24, v24, v25
	v_sub_f32_e32 v28, v28, v29
	v_mul_f32_e32 v22, v212, v22
	v_mul_f32_e32 v23, v212, v23
	v_mul_f32_e32 v24, v212, v24
	v_mul_f32_e32 v28, v212, v28
	v_cvt_pk_bf16_f32 v22, v28, v22
	v_cvt_pk_bf16_f32 v23, v23, v24
	v_pk_mul_f32 v[24:25], v[14:15], v[138:139]
	v_pk_mul_f32 v[14:15], v[14:15], v[138:139] op_sel:[1,0] op_sel_hi:[0,1]
	v_sub_f32_e32 v24, v24, v25
	v_add_f32_e32 v14, v14, v15
	v_pk_mul_f32 v[26:27], v[16:17], v[140:141]
	v_mul_f32_e32 v24, v212, v24
	v_mul_f32_e32 v14, v212, v14
	v_cvt_pk_bf16_f32 v24, v24, v14
	v_sub_f32_e32 v14, v26, v27
	v_mul_f32_e32 v25, v212, v14
	v_pk_mul_f32 v[14:15], v[16:17], v[140:141] op_sel:[1,0] op_sel_hi:[0,1]
	v_add_f32_e32 v14, v14, v15
	v_mul_f32_e32 v14, v212, v14
	v_cvt_pk_bf16_f32 v25, v25, v14
	v_pk_mul_f32 v[14:15], v[18:19], v[134:135]
	v_lshl_add_u64 v[38:39], v[202:203], 0, s[18:19]
	v_sub_f32_e32 v14, v14, v15
	global_store_dwordx4 v[38:39], v[22:25], off offset:256 sc1
	v_pk_mul_f32 v[16:17], v[20:21], v[136:137]
	s_nop 0
	v_mul_f32_e32 v24, v212, v14
	v_pk_mul_f32 v[14:15], v[18:19], v[134:135] op_sel:[1,0] op_sel_hi:[0,1]
	v_add_f32_e32 v14, v14, v15
	v_sub_f32_e32 v15, v16, v17
	v_pk_mul_f32 v[16:17], v[20:21], v[136:137] op_sel:[1,0] op_sel_hi:[0,1]
	v_add_f32_e32 v16, v16, v17
	v_mul_f32_e32 v14, v212, v14
	v_mul_f32_e32 v15, v212, v15
	v_mul_f32_e32 v16, v212, v16
	v_cvt_pk_bf16_f32 v14, v24, v14
	v_cvt_pk_bf16_f32 v15, v15, v16
	v_pk_mul_f32 v[16:17], v[10:11], v[130:131]
	v_pk_mul_f32 v[10:11], v[10:11], v[130:131] op_sel:[1,0] op_sel_hi:[0,1]
	v_sub_f32_e32 v16, v16, v17
	v_add_f32_e32 v10, v10, v11
	v_pk_mul_f32 v[18:19], v[12:13], v[132:133]
	v_mul_f32_e32 v16, v212, v16
	v_mul_f32_e32 v10, v212, v10
	v_cvt_pk_bf16_f32 v16, v16, v10
	v_sub_f32_e32 v10, v18, v19
	v_mul_f32_e32 v17, v212, v10
	v_pk_mul_f32 v[10:11], v[12:13], v[132:133] op_sel:[1,0] op_sel_hi:[0,1]
	v_add_f32_e32 v10, v10, v11
	v_mul_f32_e32 v10, v212, v10
	v_cvt_pk_bf16_f32 v17, v17, v10
	v_add_co_u32_e32 v10, vcc, s80, v202
	v_pk_mul_f32 v[12:13], v[6:7], v[134:135]
	s_nop 0
	v_addc_co_u32_e32 v11, vcc, 0, v203, vcc
	global_store_dwordx4 v[10:11], v[14:17], off sc1
	v_pk_mul_f32 v[10:11], v[8:9], v[136:137]
	v_pk_mul_f32 v[6:7], v[6:7], v[134:135] op_sel:[1,0] op_sel_hi:[0,1]
	v_pk_mul_f32 v[8:9], v[8:9], v[136:137] op_sel:[1,0] op_sel_hi:[0,1]
	v_add_f32_e32 v6, v6, v7
	v_sub_f32_e32 v7, v10, v11
	v_add_f32_e32 v8, v8, v9
	v_sub_f32_e32 v12, v12, v13
	v_mul_f32_e32 v6, v212, v6
	v_mul_f32_e32 v7, v212, v7
	v_mul_f32_e32 v8, v212, v8
	v_mul_f32_e32 v12, v212, v12
	v_cvt_pk_bf16_f32 v6, v12, v6
	v_cvt_pk_bf16_f32 v7, v7, v8
	v_pk_mul_f32 v[8:9], v[2:3], v[130:131]
	v_pk_mul_f32 v[2:3], v[2:3], v[130:131] op_sel:[1,0] op_sel_hi:[0,1]
	v_sub_f32_e32 v8, v8, v9
	v_add_f32_e32 v2, v2, v3
	v_pk_mul_f32 v[10:11], v[4:5], v[132:133]
	v_mul_f32_e32 v8, v212, v8
	v_mul_f32_e32 v2, v212, v2
	v_cvt_pk_bf16_f32 v8, v8, v2
	v_sub_f32_e32 v2, v10, v11
	v_mul_f32_e32 v9, v212, v2
	v_pk_mul_f32 v[2:3], v[4:5], v[132:133] op_sel:[1,0] op_sel_hi:[0,1]
	v_lshl_add_u64 v[22:23], v[202:203], 0, s[22:23]
	v_add_f32_e32 v2, v2, v3
	v_mul_f32_e32 v2, v212, v2
	v_cvt_pk_bf16_f32 v9, v9, v2
	global_store_dwordx4 v[22:23], v[6:9], off offset:256 sc1
	s_andn2_b64 vcc, exec, s[2:3]
	s_mov_b64 s[2:3], -1
	s_cbranch_vccnz .LBB0_220
	s_branch .LBB0_236

.LBB0_230:
	s_cmp_gt_u32 s84, 31
	s_cbranch_scc0 .LBB0_232
	s_lshl_b32 s0, s84, 8
	v_or_b32_e32 v138, v200, v206
	v_pk_mul_f32 v[134:135], v[128:129], v[124:125]
	v_pk_mul_f32 v[132:133], v[126:127], v[122:123]
	v_lshl_add_u64 v[130:131], v[190:191], 0, s[0:1]
	s_mov_b64 s[50:51], 0x245fe000
	v_ashrrev_i32_e32 v139, 31, v138
	v_cvt_pk_bf16_f32 v132, v132, v133
	v_cvt_pk_bf16_f32 v133, v134, v135
	v_pk_mul_f32 v[134:135], v[110:111], v[106:107]
	v_lshl_add_u64 v[136:137], v[130:131], 0, s[50:51]
	v_lshlrev_b64 v[130:131], 12, v[138:139]
	v_pk_mul_f32 v[140:141], v[112:113], v[108:109]
	v_cvt_pk_bf16_f32 v134, v134, v135
	v_lshl_add_u64 v[130:131], v[136:137], 0, v[130:131]
	v_cvt_pk_bf16_f32 v135, v140, v141
	v_permlane16_swap_b32_e32 v132, v134
	v_permlane16_swap_b32_e32 v133, v135
	global_store_dwordx4 v[130:131], v[132:135], off sc1
	v_pk_mul_f32 v[140:141], v[104:105], v[100:101]
	s_mov_b64 s[50:51], 0
	v_pk_mul_f32 v[134:135], v[120:121], v[116:117]
	v_pk_mul_f32 v[132:133], v[118:119], v[114:115]
	s_nop 0
	v_cvt_pk_bf16_f32 v132, v132, v133
	v_cvt_pk_bf16_f32 v133, v134, v135
	v_pk_mul_f32 v[134:135], v[102:103], v[98:99]
	s_nop 0
	v_cvt_pk_bf16_f32 v134, v134, v135
	v_cvt_pk_bf16_f32 v135, v140, v141
	s_nop 0
	v_permlane16_swap_b32_e32 v132, v134
	v_permlane16_swap_b32_e32 v133, v135
	global_store_dwordx4 v[130:131], v[132:135], off offset:128 sc1
	s_nop 1
	v_or_b32_e32 v132, 32, v138
	v_ashrrev_i32_e32 v133, 31, v132
	v_lshlrev_b64 v[132:133], 12, v[132:133]
	v_lshl_add_u64 v[136:137], v[136:137], 0, v[132:133]
	v_pk_mul_f32 v[134:135], v[96:97], v[92:93]
	v_pk_mul_f32 v[132:133], v[94:95], v[90:91]
	v_pk_mul_f32 v[138:139], v[80:81], v[76:77]
	v_cvt_pk_bf16_f32 v132, v132, v133
	v_cvt_pk_bf16_f32 v133, v134, v135
	v_pk_mul_f32 v[134:135], v[78:79], v[74:75]
	s_nop 0
	v_cvt_pk_bf16_f32 v134, v134, v135
	v_cvt_pk_bf16_f32 v135, v138, v139
	v_pk_mul_f32 v[138:139], v[72:73], v[68:69]
	v_permlane16_swap_b32_e32 v132, v134
	v_permlane16_swap_b32_e32 v133, v135
	global_store_dwordx4 v[136:137], v[132:135], off sc1
	s_nop 1
	v_pk_mul_f32 v[134:135], v[88:89], v[84:85]
	v_pk_mul_f32 v[132:133], v[86:87], v[82:83]
	s_nop 0
	v_cvt_pk_bf16_f32 v132, v132, v133
	v_cvt_pk_bf16_f32 v133, v134, v135
	v_pk_mul_f32 v[134:135], v[70:71], v[66:67]
	s_nop 0
	v_cvt_pk_bf16_f32 v134, v134, v135
	v_cvt_pk_bf16_f32 v135, v138, v139
	v_pk_mul_f32 v[138:139], v[52:53], v[44:45]
	v_permlane16_swap_b32_e32 v132, v134
	v_permlane16_swap_b32_e32 v133, v135
	global_store_dwordx4 v[136:137], v[132:135], off offset:128 sc1
	v_lshl_add_u64 v[136:137], v[130:131], 0, s[16:17]
	s_nop 0
	v_pk_mul_f32 v[134:135], v[64:65], v[60:61]
	v_pk_mul_f32 v[132:133], v[62:63], v[58:59]
	s_nop 0
	v_cvt_pk_bf16_f32 v132, v132, v133
	v_cvt_pk_bf16_f32 v133, v134, v135
	v_pk_mul_f32 v[134:135], v[50:51], v[42:43]
	s_nop 0
	v_cvt_pk_bf16_f32 v134, v134, v135
	v_cvt_pk_bf16_f32 v135, v138, v139
	v_add_co_u32_e32 v138, vcc, s67, v130
	v_permlane16_swap_b32_e32 v132, v134
	v_permlane16_swap_b32_e32 v133, v135
	v_addc_co_u32_e32 v139, vcc, 0, v131, vcc
	global_store_dwordx4 v[138:139], v[132:135], off sc1
	v_pk_mul_f32 v[138:139], v[40:41], v[32:33]
	s_nop 0
	v_pk_mul_f32 v[134:135], v[56:57], v[48:49]
	v_pk_mul_f32 v[132:133], v[54:55], v[46:47]
	s_nop 0
	v_cvt_pk_bf16_f32 v132, v132, v133
	v_cvt_pk_bf16_f32 v133, v134, v135
	v_pk_mul_f32 v[134:135], v[38:39], v[30:31]
	s_nop 0
	v_cvt_pk_bf16_f32 v134, v134, v135
	v_cvt_pk_bf16_f32 v135, v138, v139
	v_pk_mul_f32 v[138:139], v[20:21], v[12:13]
	v_permlane16_swap_b32_e32 v132, v134
	v_permlane16_swap_b32_e32 v133, v135
	global_store_dwordx4 v[136:137], v[132:135], off offset:128 sc1
	v_lshl_add_u64 v[136:137], v[130:131], 0, s[18:19]
	v_add_co_u32_e32 v130, vcc, s76, v130
	v_pk_mul_f32 v[134:135], v[36:37], v[28:29]
	v_pk_mul_f32 v[132:133], v[34:35], v[26:27]
	v_addc_co_u32_e32 v131, vcc, 0, v131, vcc
	v_cvt_pk_bf16_f32 v132, v132, v133
	v_cvt_pk_bf16_f32 v133, v134, v135
	v_pk_mul_f32 v[134:135], v[18:19], v[10:11]
	s_nop 0
	v_cvt_pk_bf16_f32 v134, v134, v135
	v_cvt_pk_bf16_f32 v135, v138, v139
	s_nop 0
	v_permlane16_swap_b32_e32 v132, v134
	v_permlane16_swap_b32_e32 v133, v135
	global_store_dwordx4 v[130:131], v[132:135], off sc1
	v_pk_mul_f32 v[130:131], v[22:23], v[14:15]
	s_nop 0
	v_pk_mul_f32 v[132:133], v[24:25], v[16:17]
	v_cvt_pk_bf16_f32 v130, v130, v131
	v_pk_mul_f32 v[134:135], v[8:9], v[4:5]
	v_cvt_pk_bf16_f32 v131, v132, v133
	v_pk_mul_f32 v[132:133], v[6:7], v[2:3]
	s_nop 0
	v_cvt_pk_bf16_f32 v132, v132, v133
	v_cvt_pk_bf16_f32 v133, v134, v135
	s_nop 0
	v_permlane16_swap_b32_e32 v130, v132
	v_permlane16_swap_b32_e32 v131, v133
	global_store_dwordx4 v[136:137], v[130:133], off offset:128 sc1
.LBB0_232:
	s_andn2_b64 vcc, exec, s[50:51]
	s_cbranch_vccnz .LBB0_234
	s_cmp_lt_u32 s84, 24
	s_mov_b32 s0, 0x20600000
	s_cselect_b32 s0, s0, 0x22600000
	s_add_u32 s0, s74, s0
	s_addc_u32 s41, s75, 0
	s_lshl_b32 s43, s84, 9
	s_and_b32 s43, s43, 0xe00
	s_add_u32 s0, s0, s43
	s_addc_u32 s41, s41, 0
	s_lshl_b32 s43, s61, 1
	s_add_u32 s50, s0, s43
	s_addc_u32 s51, s41, 0
	v_lshlrev_b32_e32 v186, 1, v188
	v_ashrrev_i32_e32 v201, 31, v200
	v_lshl_add_u64 v[136:137], s[50:51], 0, v[186:187]
	v_lshlrev_b64 v[130:131], 12, v[200:201]
	v_lshl_add_u64 v[130:131], v[136:137], 0, v[130:131]
	v_cvt_pk_bf16_f32 v132, v126, v127
	v_cvt_pk_bf16_f32 v133, v128, v129
	v_cvt_pk_bf16_f32 v134, v122, v123
	v_cvt_pk_bf16_f32 v135, v124, v125
	global_store_dwordx4 v[130:131], v[132:135], off sc1
	s_nop 1
	v_cvt_pk_bf16_f32 v132, v118, v119
	v_cvt_pk_bf16_f32 v133, v120, v121
	v_cvt_pk_bf16_f32 v134, v114, v115
	v_cvt_pk_bf16_f32 v135, v116, v117
	global_store_dwordx4 v[130:131], v[132:135], off offset:256 sc1
	s_nop 1
	v_or_b32_e32 v132, 16, v200
	v_ashrrev_i32_e32 v133, 31, v132
	v_lshlrev_b64 v[132:133], 12, v[132:133]
	v_lshl_add_u64 v[138:139], v[136:137], 0, v[132:133]
	v_cvt_pk_bf16_f32 v132, v110, v111
	v_cvt_pk_bf16_f32 v133, v112, v113
	v_cvt_pk_bf16_f32 v134, v106, v107
	v_cvt_pk_bf16_f32 v135, v108, v109
	global_store_dwordx4 v[138:139], v[132:135], off sc1
	s_nop 1
	v_cvt_pk_bf16_f32 v132, v102, v103
	v_cvt_pk_bf16_f32 v133, v104, v105
	v_cvt_pk_bf16_f32 v134, v98, v99
	v_cvt_pk_bf16_f32 v135, v100, v101
	global_store_dwordx4 v[138:139], v[132:135], off offset:256 sc1
	s_nop 1
	v_or_b32_e32 v132, 32, v200
	v_ashrrev_i32_e32 v133, 31, v132
	v_lshlrev_b64 v[132:133], 12, v[132:133]
	v_lshl_add_u64 v[138:139], v[136:137], 0, v[132:133]
	v_cvt_pk_bf16_f32 v132, v94, v95
	v_cvt_pk_bf16_f32 v133, v96, v97
	v_cvt_pk_bf16_f32 v134, v90, v91
	v_cvt_pk_bf16_f32 v135, v92, v93
	global_store_dwordx4 v[138:139], v[132:135], off sc1
	s_nop 1
	v_cvt_pk_bf16_f32 v132, v86, v87
	v_cvt_pk_bf16_f32 v133, v88, v89
	v_cvt_pk_bf16_f32 v134, v82, v83
	v_cvt_pk_bf16_f32 v135, v84, v85
	global_store_dwordx4 v[138:139], v[132:135], off offset:256 sc1
	v_add_co_u32_e32 v138, vcc, s67, v130
	s_nop 0
	v_or_b32_e32 v132, 48, v200
	v_ashrrev_i32_e32 v133, 31, v132
	v_lshlrev_b64 v[132:133], 12, v[132:133]
	v_lshl_add_u64 v[136:137], v[136:137], 0, v[132:133]
	v_cvt_pk_bf16_f32 v132, v78, v79
	v_cvt_pk_bf16_f32 v133, v80, v81
	v_cvt_pk_bf16_f32 v134, v74, v75
	v_cvt_pk_bf16_f32 v135, v76, v77
	global_store_dwordx4 v[136:137], v[132:135], off sc1
	v_addc_co_u32_e32 v139, vcc, 0, v131, vcc
	s_nop 0
	v_cvt_pk_bf16_f32 v132, v70, v71
	v_cvt_pk_bf16_f32 v133, v72, v73
	v_cvt_pk_bf16_f32 v134, v66, v67
	v_cvt_pk_bf16_f32 v135, v68, v69
	global_store_dwordx4 v[136:137], v[132:135], off offset:256 sc1
	v_lshl_add_u64 v[136:137], v[130:131], 0, s[16:17]
	s_nop 0
	v_cvt_pk_bf16_f32 v132, v62, v63
	v_cvt_pk_bf16_f32 v133, v64, v65
	v_cvt_pk_bf16_f32 v134, v58, v59
	v_cvt_pk_bf16_f32 v135, v60, v61
	global_store_dwordx4 v[138:139], v[132:135], off sc1
	v_add_co_u32_e32 v138, vcc, s77, v130
	s_nop 0
	v_cvt_pk_bf16_f32 v132, v54, v55
	v_cvt_pk_bf16_f32 v133, v56, v57
	v_cvt_pk_bf16_f32 v134, v46, v47
	v_cvt_pk_bf16_f32 v135, v48, v49
	global_store_dwordx4 v[136:137], v[132:135], off offset:256 sc1
	v_addc_co_u32_e32 v139, vcc, 0, v131, vcc
	s_nop 0
	v_cvt_pk_bf16_f32 v132, v50, v51
	v_cvt_pk_bf16_f32 v133, v52, v53
	v_cvt_pk_bf16_f32 v134, v42, v43
	v_cvt_pk_bf16_f32 v135, v44, v45
	v_lshl_add_u64 v[136:137], v[130:131], 0, s[20:21]
	global_store_dwordx4 v[138:139], v[132:135], off sc1
	v_add_co_u32_e32 v138, vcc, s76, v130
	s_nop 0
	v_cvt_pk_bf16_f32 v132, v38, v39
	v_cvt_pk_bf16_f32 v133, v40, v41
	v_cvt_pk_bf16_f32 v134, v30, v31
	v_cvt_pk_bf16_f32 v135, v32, v33
	global_store_dwordx4 v[136:137], v[132:135], off offset:256 sc1
	v_lshl_add_u64 v[136:137], v[130:131], 0, s[18:19]
	v_addc_co_u32_e32 v139, vcc, 0, v131, vcc
	v_cvt_pk_bf16_f32 v132, v34, v35
	v_cvt_pk_bf16_f32 v133, v36, v37
	v_cvt_pk_bf16_f32 v134, v26, v27
	v_cvt_pk_bf16_f32 v135, v28, v29
	global_store_dwordx4 v[138:139], v[132:135], off sc1
	s_nop 1
	v_cvt_pk_bf16_f32 v132, v22, v23
	v_cvt_pk_bf16_f32 v133, v24, v25
	v_cvt_pk_bf16_f32 v134, v14, v15
	v_cvt_pk_bf16_f32 v135, v16, v17
	global_store_dwordx4 v[136:137], v[132:135], off offset:256 sc1
	v_lshl_add_u64 v[136:137], v[130:131], 0, s[22:23]
	v_add_co_u32_e32 v130, vcc, s80, v130
	v_cvt_pk_bf16_f32 v132, v18, v19
	v_cvt_pk_bf16_f32 v133, v20, v21
	v_cvt_pk_bf16_f32 v134, v10, v11
	v_cvt_pk_bf16_f32 v135, v12, v13
	s_nop 1
	v_addc_co_u32_e32 v131, vcc, 0, v131, vcc
	global_store_dwordx4 v[130:131], v[132:135], off sc1
	v_cvt_pk_bf16_f32 v130, v6, v7
	v_cvt_pk_bf16_f32 v131, v8, v9
	s_nop 1
	v_cvt_pk_bf16_f32 v132, v2, v3
	v_cvt_pk_bf16_f32 v133, v4, v5
	global_store_dwordx4 v[136:137], v[130:133], off offset:256 sc1

.LBB0_695:
	s_or_b64 exec, exec, s[16:17]
	v_cvt_pk_bf16_f32 v130, v90, v91
	s_waitcnt lgkmcnt(0)
	v_cvt_pk_bf16_f32 v131, v92, v93
	s_add_u32 s16, s0, 0x10000
	v_cndmask_b32_e64 v132, v130, v241, s[2:3]
	v_cvt_pk_bf16_f32 v130, v98, v99
	v_cndmask_b32_e64 v133, v131, v241, s[2:3]
	v_cvt_pk_bf16_f32 v131, v100, v101
	v_cndmask_b32_e64 v134, v130, v241, s[2:3]
	v_add_u32_e32 v130, s18, v227
	v_cndmask_b32_e64 v135, v131, v241, s[2:3]
	v_ashrrev_i32_e32 v131, 31, v130
	v_lshlrev_b64 v[208:209], 13, v[130:131]
	v_permlane16_swap_b32_e32 v132, v134
	v_permlane16_swap_b32_e32 v133, v135
	v_lshl_add_u64 v[130:131], v[190:191], 0, v[208:209]
	global_store_dwordx4 v[130:131], v[132:135], off sc1
	s_addc_u32 s17, s1, 0
	s_add_u32 s0, s0, 0xc000
	v_cvt_pk_bf16_f32 v132, v102, v103
	v_cvt_pk_bf16_f32 v133, v104, v105
	s_addc_u32 s1, s1, 0
	v_cndmask_b32_e64 v134, v132, v241, s[2:3]
	v_cvt_pk_bf16_f32 v132, v110, v111
	v_cndmask_b32_e64 v135, v133, v241, s[2:3]
	v_cvt_pk_bf16_f32 v133, v112, v113
	v_cndmask_b32_e64 v136, v132, v241, s[2:3]
	v_add_u32_e32 v132, s18, v228
	v_cndmask_b32_e64 v137, v133, v241, s[2:3]
	v_ashrrev_i32_e32 v133, 31, v132
	v_lshlrev_b64 v[206:207], 13, v[132:133]
	v_permlane16_swap_b32_e32 v134, v136
	v_permlane16_swap_b32_e32 v135, v137
	v_lshl_add_u64 v[132:133], v[190:191], 0, v[206:207]
	global_store_dwordx4 v[132:133], v[134:137], off sc1
	v_or_b32_e32 v242, s19, v231
	v_add_u32_e32 v210, s18, v242
	v_cvt_pk_bf16_f32 v134, v114, v115
	v_cvt_pk_bf16_f32 v135, v116, v117
	v_ashrrev_i32_e32 v211, 31, v210
	v_cndmask_b32_e64 v136, v134, v241, s[2:3]
	v_cvt_pk_bf16_f32 v134, v118, v119
	v_cndmask_b32_e64 v137, v135, v241, s[2:3]
	v_cvt_pk_bf16_f32 v135, v120, v121
	v_cndmask_b32_e64 v138, v134, v241, s[2:3]
	v_add_u32_e32 v134, s18, v229
	v_cndmask_b32_e64 v139, v135, v241, s[2:3]
	v_ashrrev_i32_e32 v135, 31, v134
	v_lshlrev_b64 v[204:205], 13, v[134:135]
	v_permlane16_swap_b32_e32 v136, v138
	v_permlane16_swap_b32_e32 v137, v139
	v_lshl_add_u64 v[134:135], v[190:191], 0, v[204:205]
	global_store_dwordx4 v[134:135], v[136:139], off sc1
	v_lshlrev_b64 v[210:211], 6, v[210:211]
	v_lshl_add_u64 v[210:211], v[184:185], 0, v[210:211]
	v_cvt_pk_bf16_f32 v136, v122, v123
	v_cvt_pk_bf16_f32 v137, v124, v125
	s_nop 0
	v_cndmask_b32_e64 v138, v136, v241, s[2:3]
	v_cvt_pk_bf16_f32 v136, v126, v127
	v_cndmask_b32_e64 v139, v137, v241, s[2:3]
	v_cvt_pk_bf16_f32 v137, v128, v129
	v_cndmask_b32_e64 v140, v136, v241, s[2:3]
	v_add_u32_e32 v136, s18, v230
	v_cndmask_b32_e64 v141, v137, v241, s[2:3]
	v_ashrrev_i32_e32 v137, 31, v136
	v_lshlrev_b64 v[202:203], 13, v[136:137]
	v_permlane16_swap_b32_e32 v138, v140
	v_permlane16_swap_b32_e32 v139, v141
	v_lshl_add_u64 v[136:137], v[190:191], 0, v[202:203]
	global_store_dwordx4 v[136:137], v[138:141], off sc1
	s_nop 1
	v_cvt_pk_bf16_f32 v138, v58, v59
	v_cvt_pk_bf16_f32 v139, v60, v61
	v_cvt_pk_bf16_f32 v140, v66, v67
	v_cvt_pk_bf16_f32 v141, v68, v69
	s_nop 0
	v_cndmask_b32_e64 v139, v139, v241, s[2:3]
	v_cndmask_b32_e64 v138, v138, v241, s[2:3]
	v_cndmask_b32_e64 v141, v141, v241, s[2:3]
	v_cndmask_b32_e64 v140, v140, v241, s[2:3]
	s_nop 1
	v_permlane16_swap_b32_e32 v138, v140
	v_permlane16_swap_b32_e32 v139, v141
	global_store_dwordx4 v[130:131], v[138:141], off offset:32 sc1
	s_nop 1
	v_cvt_pk_bf16_f32 v138, v70, v71
	v_cvt_pk_bf16_f32 v139, v72, v73
	v_cvt_pk_bf16_f32 v140, v78, v79
	v_cvt_pk_bf16_f32 v141, v80, v81
	s_nop 0
	v_cndmask_b32_e64 v139, v139, v241, s[2:3]
	v_cndmask_b32_e64 v138, v138, v241, s[2:3]
	v_cndmask_b32_e64 v141, v141, v241, s[2:3]
	v_cndmask_b32_e64 v140, v140, v241, s[2:3]
	s_nop 1
	v_permlane16_swap_b32_e32 v138, v140
	v_permlane16_swap_b32_e32 v139, v141
	global_store_dwordx4 v[132:133], v[138:141], off offset:32 sc1
	s_nop 1
	v_cvt_pk_bf16_f32 v138, v82, v83
	v_cvt_pk_bf16_f32 v139, v84, v85
	v_cvt_pk_bf16_f32 v140, v86, v87
	v_cvt_pk_bf16_f32 v141, v88, v89
	s_nop 0
	v_cndmask_b32_e64 v139, v139, v241, s[2:3]
	v_cndmask_b32_e64 v138, v138, v241, s[2:3]
	v_cndmask_b32_e64 v141, v141, v241, s[2:3]
	v_cndmask_b32_e64 v140, v140, v241, s[2:3]
	s_nop 1
	v_permlane16_swap_b32_e32 v138, v140
	v_permlane16_swap_b32_e32 v139, v141
	global_store_dwordx4 v[134:135], v[138:141], off offset:32 sc1
	s_nop 1
	v_cvt_pk_bf16_f32 v138, v94, v95
	v_cvt_pk_bf16_f32 v139, v96, v97
	v_cvt_pk_bf16_f32 v140, v106, v107
	v_cvt_pk_bf16_f32 v141, v108, v109
	s_nop 0
	v_cndmask_b32_e64 v139, v139, v241, s[2:3]
	v_cndmask_b32_e64 v138, v138, v241, s[2:3]
	v_cndmask_b32_e64 v141, v141, v241, s[2:3]
	v_cndmask_b32_e64 v140, v140, v241, s[2:3]
	s_nop 1
	v_permlane16_swap_b32_e32 v138, v140
	v_permlane16_swap_b32_e32 v139, v141
	global_store_dwordx4 v[136:137], v[138:141], off offset:32 sc1
	s_nop 1
	v_cvt_pk_bf16_f32 v138, v26, v27
	v_cvt_pk_bf16_f32 v139, v28, v29
	v_cvt_pk_bf16_f32 v140, v34, v35
	v_cvt_pk_bf16_f32 v141, v36, v37
	s_nop 0
	v_cndmask_b32_e64 v139, v139, v241, s[2:3]
	v_cndmask_b32_e64 v138, v138, v241, s[2:3]
	v_cndmask_b32_e64 v141, v141, v241, s[2:3]
	v_cndmask_b32_e64 v140, v140, v241, s[2:3]
	s_nop 1
	v_permlane16_swap_b32_e32 v138, v140
	v_permlane16_swap_b32_e32 v139, v141
	global_store_dwordx4 v[130:131], v[138:141], off offset:256 sc1
	s_nop 1
	v_cvt_pk_bf16_f32 v138, v38, v39
	v_cvt_pk_bf16_f32 v139, v40, v41
	v_cvt_pk_bf16_f32 v140, v46, v47
	v_cvt_pk_bf16_f32 v141, v48, v49
	s_nop 0
	v_cndmask_b32_e64 v139, v139, v241, s[2:3]
	v_cndmask_b32_e64 v138, v138, v241, s[2:3]
	v_cndmask_b32_e64 v141, v141, v241, s[2:3]
	v_cndmask_b32_e64 v140, v140, v241, s[2:3]
	s_nop 1
	v_permlane16_swap_b32_e32 v138, v140
	v_permlane16_swap_b32_e32 v139, v141
	global_store_dwordx4 v[132:133], v[138:141], off offset:256 sc1
	s_nop 1
	v_cvt_pk_bf16_f32 v138, v50, v51
	v_cvt_pk_bf16_f32 v139, v52, v53
	v_cvt_pk_bf16_f32 v140, v54, v55
	v_cvt_pk_bf16_f32 v141, v56, v57
	s_nop 0
	v_cndmask_b32_e64 v139, v139, v241, s[2:3]
	v_cndmask_b32_e64 v138, v138, v241, s[2:3]
	v_cndmask_b32_e64 v141, v141, v241, s[2:3]
	v_cndmask_b32_e64 v140, v140, v241, s[2:3]
	s_nop 1
	v_permlane16_swap_b32_e32 v138, v140
	v_permlane16_swap_b32_e32 v139, v141
	global_store_dwordx4 v[134:135], v[138:141], off offset:256 sc1
	s_nop 1
	v_cvt_pk_bf16_f32 v138, v62, v63
	v_cvt_pk_bf16_f32 v139, v64, v65
	v_cvt_pk_bf16_f32 v140, v74, v75
	v_cvt_pk_bf16_f32 v141, v76, v77
	s_nop 0
	v_cndmask_b32_e64 v139, v139, v241, s[2:3]
	v_cndmask_b32_e64 v138, v138, v241, s[2:3]
	v_cndmask_b32_e64 v141, v141, v241, s[2:3]
	v_cndmask_b32_e64 v140, v140, v241, s[2:3]
	s_nop 1
	v_permlane16_swap_b32_e32 v138, v140
	v_permlane16_swap_b32_e32 v139, v141
	global_store_dwordx4 v[136:137], v[138:141], off offset:256 sc1
	s_nop 1
	v_cvt_pk_bf16_f32 v138, v2, v3
	v_cvt_pk_bf16_f32 v139, v4, v5
	v_cvt_pk_bf16_f32 v140, v6, v7
	v_cvt_pk_bf16_f32 v141, v8, v9
	s_nop 0
	v_cndmask_b32_e64 v139, v139, v241, s[2:3]
	v_cndmask_b32_e64 v138, v138, v241, s[2:3]
	v_cndmask_b32_e64 v141, v141, v241, s[2:3]
	v_cndmask_b32_e64 v140, v140, v241, s[2:3]
	s_nop 1
	v_permlane16_swap_b32_e32 v138, v140
	v_permlane16_swap_b32_e32 v139, v141
	global_store_dwordx4 v[130:131], v[138:141], off offset:288 sc1
	v_cvt_pk_bf16_f32 v130, v10, v11
	v_cvt_pk_bf16_f32 v131, v12, v13
	s_nop 1
	v_cndmask_b32_e64 v139, v131, v241, s[2:3]
	v_cndmask_b32_e64 v138, v130, v241, s[2:3]
	v_cvt_pk_bf16_f32 v130, v14, v15
	v_cvt_pk_bf16_f32 v131, v16, v17
	s_nop 0
	v_cndmask_b32_e64 v141, v131, v241, s[2:3]
	v_cndmask_b32_e64 v140, v130, v241, s[2:3]
	s_nop 1
	v_permlane16_swap_b32_e32 v138, v140
	v_permlane16_swap_b32_e32 v139, v141
	global_store_dwordx4 v[132:133], v[138:141], off offset:288 sc1
	v_cvt_pk_bf16_f32 v130, v18, v19
	v_cvt_pk_bf16_f32 v131, v20, v21
	v_cvt_pk_bf16_f32 v132, v22, v23
	v_cvt_pk_bf16_f32 v133, v24, v25
	s_nop 0
	v_cndmask_b32_e64 v131, v131, v241, s[2:3]
	v_cndmask_b32_e64 v130, v130, v241, s[2:3]
	v_cndmask_b32_e64 v133, v133, v241, s[2:3]
	v_cndmask_b32_e64 v132, v132, v241, s[2:3]
	s_nop 1
	v_permlane16_swap_b32_e32 v130, v132
	v_permlane16_swap_b32_e32 v131, v133
	global_store_dwordx4 v[134:135], v[130:133], off offset:288 sc1
	s_nop 1
	v_cvt_pk_bf16_f32 v130, v30, v31
	v_cvt_pk_bf16_f32 v131, v32, v33
	v_cvt_pk_bf16_f32 v132, v42, v43
	v_cvt_pk_bf16_f32 v133, v44, v45
	s_nop 0
	v_cndmask_b32_e64 v131, v131, v241, s[2:3]
	v_cndmask_b32_e64 v130, v130, v241, s[2:3]
	v_cndmask_b32_e64 v133, v133, v241, s[2:3]
	v_cndmask_b32_e64 v132, v132, v241, s[2:3]
	s_nop 1
	v_permlane16_swap_b32_e32 v130, v132
	v_permlane16_swap_b32_e32 v131, v133
	global_store_dwordx4 v[136:137], v[130:133], off offset:288 sc1
	global_load_dwordx4 v[174:177], v198, s[16:17]
	global_load_dwordx4 v[166:169], v198, s[0:1]
	global_load_dwordx4 v[170:173], v[188:189], off
	global_load_dwordx4 v[154:157], v[188:189], off offset:64
	global_load_dwordx4 v[162:165], v235, s[16:17]
	global_load_dwordx4 v[158:161], v235, s[0:1]
	global_load_dwordx4 v[150:153], v236, s[16:17]
	global_load_dwordx4 v[142:145], v236, s[0:1]
	global_load_dwordx4 v[146:149], v[188:189], off offset:512
	global_load_dwordx4 v[130:133], v[188:189], off offset:576
	global_load_dwordx4 v[138:141], v237, s[16:17]
	global_load_dwordx4 v[134:137], v237, s[0:1]
	s_memrealtime s[62:63]
	s_branch .LBB0_698

.LBB0_715:
	s_or_b64 exec, exec, s[16:17]
	s_and_b64 s[16:17], s[10:11], s[58:59]
	s_and_saveexec_b64 s[0:1], s[16:17]
	v_mov_b32_e32 v182, s82
	ds_write_b32 v182, v238
	s_or_b64 exec, exec, s[0:1]
	s_waitcnt vmcnt(0) lgkmcnt(0)
	s_barrier
	ds_read_b32 v182, v232
	s_waitcnt lgkmcnt(0)
	v_mov_b32_e32 v199, s82
	ds_read_b32 v199, v199
	v_pk_add_f32 v[210:211], v[176:177], 1.0 op_sel_hi:[1,0]
	v_pk_add_f32 v[212:213], v[174:175], 1.0 op_sel_hi:[1,0]
	v_pk_mul_f32 v[92:93], v[92:93], v[182:183] op_sel_hi:[1,0]
	v_pk_mul_f32 v[90:91], v[90:91], v[182:183] op_sel_hi:[1,0]
	v_pk_mul_f32 v[92:93], v[172:173], v[92:93]
	v_pk_mul_f32 v[90:91], v[170:171], v[90:91]
	v_pk_fma_f32 v[92:93], v[210:211], v[92:93], v[168:169]
	v_pk_fma_f32 v[90:91], v[212:213], v[90:91], v[166:167]
	s_waitcnt lgkmcnt(0)
	v_cmp_ne_u32_e32 vcc, 0, v199
	v_cvt_pk_bf16_f32 v91, v90, v91
	v_cvt_pk_bf16_f32 v92, v92, v93
	ds_read_b32 v90, v232 offset:64
	s_or_b64 vcc, vcc, s[2:3]
	v_cndmask_b32_e32 v175, v92, v241, vcc
	v_cndmask_b32_e32 v174, v91, v241, vcc
	s_mov_b64 s[0:1], -1
	s_waitcnt lgkmcnt(0)
	v_pk_mul_f32 v[92:93], v[100:101], v[90:91] op_sel_hi:[1,0]
	v_pk_mul_f32 v[90:91], v[98:99], v[90:91] op_sel_hi:[1,0]
	v_pk_mul_f32 v[92:93], v[172:173], v[92:93]
	v_pk_mul_f32 v[90:91], v[170:171], v[90:91]
	v_pk_fma_f32 v[92:93], v[210:211], v[92:93], v[168:169]
	v_pk_fma_f32 v[90:91], v[212:213], v[90:91], v[166:167]
	s_nop 0
	v_cvt_pk_bf16_f32 v90, v90, v91
	v_cvt_pk_bf16_f32 v91, v92, v93
	ds_read_b32 v92, v232 offset:128
	v_cndmask_b32_e32 v177, v91, v241, vcc
	v_cndmask_b32_e32 v176, v90, v241, vcc
	s_nop 1
	v_permlane16_swap_b32_e32 v174, v176
	s_waitcnt lgkmcnt(0)
	v_pk_mul_f32 v[98:99], v[104:105], v[92:93] op_sel_hi:[1,0]
	v_pk_mul_f32 v[92:93], v[102:103], v[92:93] op_sel_hi:[1,0]
	v_pk_mul_f32 v[98:99], v[172:173], v[98:99]
	v_pk_mul_f32 v[92:93], v[170:171], v[92:93]
	v_permlane16_swap_b32_e32 v175, v177
	v_lshl_add_u64 v[90:91], v[192:193], 0, v[208:209]
	v_pk_fma_f32 v[98:99], v[210:211], v[98:99], v[168:169]
	v_pk_fma_f32 v[92:93], v[212:213], v[92:93], v[166:167]
	global_store_dwordx4 v[90:91], v[174:177], off sc1
	v_cvt_pk_bf16_f32 v93, v92, v93
	v_cvt_pk_bf16_f32 v98, v98, v99
	ds_read_b32 v92, v232 offset:192
	v_cndmask_b32_e32 v99, v98, v241, vcc
	v_cndmask_b32_e32 v98, v93, v241, vcc
	s_waitcnt lgkmcnt(0)
	v_pk_mul_f32 v[100:101], v[112:113], v[92:93] op_sel_hi:[1,0]
	v_pk_mul_f32 v[92:93], v[110:111], v[92:93] op_sel_hi:[1,0]
	v_pk_mul_f32 v[100:101], v[172:173], v[100:101]
	v_pk_mul_f32 v[92:93], v[170:171], v[92:93]
	v_pk_fma_f32 v[100:101], v[210:211], v[100:101], v[168:169]
	v_pk_fma_f32 v[92:93], v[212:213], v[92:93], v[166:167]
	v_pk_add_f32 v[110:111], v[162:163], 1.0 op_sel_hi:[1,0]
	v_cvt_pk_bf16_f32 v92, v92, v93
	v_cvt_pk_bf16_f32 v93, v100, v101
	ds_read_b32 v102, v232 offset:512
	v_cndmask_b32_e32 v101, v93, v241, vcc
	v_cndmask_b32_e32 v100, v92, v241, vcc
	s_nop 1
	v_permlane16_swap_b32_e32 v98, v100
	v_permlane16_swap_b32_e32 v99, v101
	v_lshl_add_u64 v[92:93], v[192:193], 0, v[206:207]
	global_store_dwordx4 v[92:93], v[98:101], off sc1
	s_waitcnt lgkmcnt(0)
	s_nop 0
	v_pk_mul_f32 v[98:99], v[116:117], v[102:103] op_sel_hi:[1,0]
	v_pk_mul_f32 v[100:101], v[114:115], v[102:103] op_sel_hi:[1,0]
	v_pk_mul_f32 v[98:99], v[172:173], v[98:99]
	v_pk_mul_f32 v[100:101], v[170:171], v[100:101]
	v_pk_fma_f32 v[98:99], v[210:211], v[98:99], v[168:169]
	v_pk_fma_f32 v[100:101], v[212:213], v[100:101], v[166:167]
	s_nop 0
	v_cvt_pk_bf16_f32 v100, v100, v101
	v_cvt_pk_bf16_f32 v99, v98, v99
	ds_read_b32 v98, v232 offset:576
	v_cndmask_b32_e32 v101, v99, v241, vcc
	v_cndmask_b32_e32 v100, v100, v241, vcc
	s_waitcnt lgkmcnt(0)
	v_pk_mul_f32 v[102:103], v[120:121], v[98:99] op_sel_hi:[1,0]
	v_pk_mul_f32 v[98:99], v[118:119], v[98:99] op_sel_hi:[1,0]
	v_pk_mul_f32 v[102:103], v[172:173], v[102:103]
	v_pk_mul_f32 v[98:99], v[170:171], v[98:99]
	v_pk_fma_f32 v[102:103], v[210:211], v[102:103], v[168:169]
	v_pk_fma_f32 v[98:99], v[212:213], v[98:99], v[166:167]
	s_nop 0
	v_cvt_pk_bf16_f32 v98, v98, v99
	v_cvt_pk_bf16_f32 v99, v102, v103
	ds_read_b32 v104, v232 offset:640
	v_cndmask_b32_e32 v103, v99, v241, vcc
	v_cndmask_b32_e32 v102, v98, v241, vcc
	s_nop 1
	v_permlane16_swap_b32_e32 v100, v102
	v_permlane16_swap_b32_e32 v101, v103
	v_lshl_add_u64 v[98:99], v[192:193], 0, v[204:205]
	global_store_dwordx4 v[98:99], v[100:103], off sc1
	s_waitcnt lgkmcnt(0)
	s_nop 0
	v_pk_mul_f32 v[100:101], v[124:125], v[104:105] op_sel_hi:[1,0]
	v_pk_mul_f32 v[102:103], v[122:123], v[104:105] op_sel_hi:[1,0]
	v_pk_mul_f32 v[100:101], v[172:173], v[100:101]
	v_pk_mul_f32 v[102:103], v[170:171], v[102:103]
	v_pk_fma_f32 v[100:101], v[210:211], v[100:101], v[168:169]
	v_pk_fma_f32 v[102:103], v[212:213], v[102:103], v[166:167]
	s_nop 0
	v_cvt_pk_bf16_f32 v102, v102, v103
	v_cvt_pk_bf16_f32 v101, v100, v101
	ds_read_b32 v100, v232 offset:704
	v_cndmask_b32_e32 v103, v101, v241, vcc
	v_cndmask_b32_e32 v102, v102, v241, vcc
	s_waitcnt lgkmcnt(0)
	v_pk_mul_f32 v[104:105], v[128:129], v[100:101] op_sel_hi:[1,0]
	v_pk_mul_f32 v[100:101], v[126:127], v[100:101] op_sel_hi:[1,0]
	v_pk_mul_f32 v[104:105], v[172:173], v[104:105]
	v_pk_mul_f32 v[100:101], v[170:171], v[100:101]
	v_pk_fma_f32 v[104:105], v[210:211], v[104:105], v[168:169]
	v_pk_fma_f32 v[100:101], v[212:213], v[100:101], v[166:167]
	s_nop 0
	v_cvt_pk_bf16_f32 v100, v100, v101
	v_cvt_pk_bf16_f32 v101, v104, v105
	s_nop 0
	v_cndmask_b32_e32 v105, v101, v241, vcc
	v_cndmask_b32_e32 v104, v100, v241, vcc
	s_nop 1
	v_permlane16_swap_b32_e32 v102, v104
	v_permlane16_swap_b32_e32 v103, v105
	v_lshl_add_u64 v[100:101], v[192:193], 0, v[202:203]
	global_store_dwordx4 v[100:101], v[102:105], off sc1
	ds_read_b32 v102, v232
	s_waitcnt lgkmcnt(0)
	v_pk_mul_f32 v[60:61], v[60:61], v[102:103] op_sel_hi:[1,0]
	v_pk_mul_f32 v[58:59], v[58:59], v[102:103] op_sel_hi:[1,0]
	v_pk_add_f32 v[104:105], v[164:165], 1.0 op_sel_hi:[1,0]
	v_pk_mul_f32 v[60:61], v[156:157], v[60:61]
	v_pk_mul_f32 v[58:59], v[154:155], v[58:59]
	v_pk_fma_f32 v[60:61], v[104:105], v[60:61], v[160:161]
	v_pk_fma_f32 v[58:59], v[110:111], v[58:59], v[158:159]
	s_nop 0
	v_cvt_pk_bf16_f32 v58, v58, v59
	v_cvt_pk_bf16_f32 v59, v60, v61
	ds_read_b32 v60, v232 offset:64
	v_cndmask_b32_e32 v59, v59, v241, vcc
	v_cndmask_b32_e32 v58, v58, v241, vcc
	s_waitcnt lgkmcnt(0)
	v_pk_mul_f32 v[68:69], v[68:69], v[60:61] op_sel_hi:[1,0]
	v_pk_mul_f32 v[60:61], v[66:67], v[60:61] op_sel_hi:[1,0]
	v_pk_mul_f32 v[66:67], v[156:157], v[68:69]
	v_pk_mul_f32 v[60:61], v[154:155], v[60:61]
	v_pk_fma_f32 v[66:67], v[104:105], v[66:67], v[160:161]
	v_pk_fma_f32 v[60:61], v[110:111], v[60:61], v[158:159]
	s_nop 0
	v_cvt_pk_bf16_f32 v60, v60, v61
	v_cvt_pk_bf16_f32 v61, v66, v67
	ds_read_b32 v66, v232 offset:128
	v_cndmask_b32_e32 v61, v61, v241, vcc
	v_cndmask_b32_e32 v60, v60, v241, vcc
	s_nop 1
	v_permlane16_swap_b32_e32 v58, v60
	v_permlane16_swap_b32_e32 v59, v61
	global_store_dwordx4 v[90:91], v[58:61], off offset:32 sc1
	s_waitcnt lgkmcnt(0)
	s_nop 0
	v_pk_mul_f32 v[58:59], v[72:73], v[66:67] op_sel_hi:[1,0]
	v_pk_mul_f32 v[60:61], v[70:71], v[66:67] op_sel_hi:[1,0]
	v_pk_mul_f32 v[58:59], v[156:157], v[58:59]
	v_pk_mul_f32 v[60:61], v[154:155], v[60:61]
	v_pk_fma_f32 v[58:59], v[104:105], v[58:59], v[160:161]
	v_pk_fma_f32 v[60:61], v[110:111], v[60:61], v[158:159]
	s_nop 0
	v_cvt_pk_bf16_f32 v61, v60, v61
	v_cvt_pk_bf16_f32 v58, v58, v59
	ds_read_b32 v60, v232 offset:192
	v_cndmask_b32_e32 v59, v58, v241, vcc
	v_cndmask_b32_e32 v58, v61, v241, vcc
	s_waitcnt lgkmcnt(0)
	v_pk_mul_f32 v[66:67], v[80:81], v[60:61] op_sel_hi:[1,0]
	v_pk_mul_f32 v[60:61], v[78:79], v[60:61] op_sel_hi:[1,0]
	v_pk_mul_f32 v[66:67], v[156:157], v[66:67]
	v_pk_mul_f32 v[60:61], v[154:155], v[60:61]
	v_pk_fma_f32 v[66:67], v[104:105], v[66:67], v[160:161]
	v_pk_fma_f32 v[60:61], v[110:111], v[60:61], v[158:159]
	s_nop 0
	v_cvt_pk_bf16_f32 v60, v60, v61
	v_cvt_pk_bf16_f32 v61, v66, v67
	ds_read_b32 v66, v232 offset:512
	v_cndmask_b32_e32 v61, v61, v241, vcc
	v_cndmask_b32_e32 v60, v60, v241, vcc
	s_nop 1
	v_permlane16_swap_b32_e32 v58, v60
	v_permlane16_swap_b32_e32 v59, v61
	global_store_dwordx4 v[92:93], v[58:61], off offset:32 sc1
	s_waitcnt lgkmcnt(0)
	s_nop 0
	v_pk_mul_f32 v[58:59], v[84:85], v[66:67] op_sel_hi:[1,0]
	v_pk_mul_f32 v[60:61], v[82:83], v[66:67] op_sel_hi:[1,0]
	v_pk_mul_f32 v[58:59], v[156:157], v[58:59]
	v_pk_mul_f32 v[60:61], v[154:155], v[60:61]
	v_pk_fma_f32 v[58:59], v[104:105], v[58:59], v[160:161]
	v_pk_fma_f32 v[60:61], v[110:111], v[60:61], v[158:159]
	s_nop 0
	v_cvt_pk_bf16_f32 v61, v60, v61
	v_cvt_pk_bf16_f32 v58, v58, v59
	ds_read_b32 v60, v232 offset:576
	v_cndmask_b32_e32 v59, v58, v241, vcc
	v_cndmask_b32_e32 v58, v61, v241, vcc
	s_waitcnt lgkmcnt(0)
	v_pk_mul_f32 v[66:67], v[88:89], v[60:61] op_sel_hi:[1,0]
	v_pk_mul_f32 v[60:61], v[86:87], v[60:61] op_sel_hi:[1,0]
	v_pk_mul_f32 v[66:67], v[156:157], v[66:67]
	v_pk_mul_f32 v[60:61], v[154:155], v[60:61]
	v_pk_fma_f32 v[66:67], v[104:105], v[66:67], v[160:161]
	v_pk_fma_f32 v[60:61], v[110:111], v[60:61], v[158:159]
	s_nop 0
	v_cvt_pk_bf16_f32 v60, v60, v61
	v_cvt_pk_bf16_f32 v61, v66, v67
	ds_read_b32 v66, v232 offset:640
	v_cndmask_b32_e32 v61, v61, v241, vcc
	v_cndmask_b32_e32 v60, v60, v241, vcc
	s_nop 1
	v_permlane16_swap_b32_e32 v58, v60
	v_permlane16_swap_b32_e32 v59, v61
	global_store_dwordx4 v[98:99], v[58:61], off offset:32 sc1
	s_waitcnt lgkmcnt(0)
	s_nop 0
	v_pk_mul_f32 v[58:59], v[96:97], v[66:67] op_sel_hi:[1,0]
	v_pk_mul_f32 v[60:61], v[94:95], v[66:67] op_sel_hi:[1,0]
	v_pk_mul_f32 v[58:59], v[156:157], v[58:59]
	v_pk_mul_f32 v[60:61], v[154:155], v[60:61]
	v_pk_fma_f32 v[58:59], v[104:105], v[58:59], v[160:161]
	v_pk_fma_f32 v[60:61], v[110:111], v[60:61], v[158:159]
	s_nop 0
	v_cvt_pk_bf16_f32 v61, v60, v61
	v_cvt_pk_bf16_f32 v58, v58, v59
	ds_read_b32 v60, v232 offset:704
	v_cndmask_b32_e32 v59, v58, v241, vcc
	v_cndmask_b32_e32 v58, v61, v241, vcc
	s_waitcnt lgkmcnt(0)
	v_pk_mul_f32 v[66:67], v[108:109], v[60:61] op_sel_hi:[1,0]
	v_pk_mul_f32 v[60:61], v[106:107], v[60:61] op_sel_hi:[1,0]
	v_pk_mul_f32 v[66:67], v[156:157], v[66:67]
	v_pk_mul_f32 v[60:61], v[154:155], v[60:61]
	v_pk_fma_f32 v[66:67], v[104:105], v[66:67], v[160:161]
	v_pk_fma_f32 v[60:61], v[110:111], v[60:61], v[158:159]
	s_nop 0
	v_cvt_pk_bf16_f32 v60, v60, v61
	v_cvt_pk_bf16_f32 v61, v66, v67
	v_pk_add_f32 v[66:67], v[150:151], 1.0 op_sel_hi:[1,0]
	v_cndmask_b32_e32 v61, v61, v241, vcc
	v_cndmask_b32_e32 v60, v60, v241, vcc
	s_nop 1
	v_permlane16_swap_b32_e32 v58, v60
	v_permlane16_swap_b32_e32 v59, v61
	global_store_dwordx4 v[100:101], v[58:61], off offset:32 sc1
	ds_read_b32 v58, v232
	s_waitcnt lgkmcnt(0)
	v_pk_mul_f32 v[28:29], v[28:29], v[58:59] op_sel_hi:[1,0]
	v_pk_mul_f32 v[26:27], v[26:27], v[58:59] op_sel_hi:[1,0]
	v_pk_add_f32 v[60:61], v[152:153], 1.0 op_sel_hi:[1,0]
	v_pk_mul_f32 v[28:29], v[148:149], v[28:29]
	v_pk_mul_f32 v[26:27], v[146:147], v[26:27]
	v_pk_fma_f32 v[28:29], v[60:61], v[28:29], v[144:145]
	v_pk_fma_f32 v[26:27], v[66:67], v[26:27], v[142:143]
	s_nop 0
	v_cvt_pk_bf16_f32 v26, v26, v27
	v_cvt_pk_bf16_f32 v27, v28, v29
	ds_read_b32 v28, v232 offset:64
	v_cndmask_b32_e32 v27, v27, v241, vcc
	v_cndmask_b32_e32 v26, v26, v241, vcc
	s_waitcnt lgkmcnt(0)
	v_pk_mul_f32 v[36:37], v[36:37], v[28:29] op_sel_hi:[1,0]
	v_pk_mul_f32 v[28:29], v[34:35], v[28:29] op_sel_hi:[1,0]
	v_pk_mul_f32 v[34:35], v[148:149], v[36:37]
	v_pk_mul_f32 v[28:29], v[146:147], v[28:29]
	v_pk_fma_f32 v[34:35], v[60:61], v[34:35], v[144:145]
	v_pk_fma_f32 v[28:29], v[66:67], v[28:29], v[142:143]
	s_nop 0
	v_cvt_pk_bf16_f32 v28, v28, v29
	v_cvt_pk_bf16_f32 v29, v34, v35
	ds_read_b32 v34, v232 offset:128
	v_cndmask_b32_e32 v29, v29, v241, vcc
	v_cndmask_b32_e32 v28, v28, v241, vcc
	s_nop 1
	v_permlane16_swap_b32_e32 v26, v28
	v_permlane16_swap_b32_e32 v27, v29
	global_store_dwordx4 v[90:91], v[26:29], off offset:256 sc1
	s_waitcnt lgkmcnt(0)
	s_nop 0
	v_pk_mul_f32 v[26:27], v[40:41], v[34:35] op_sel_hi:[1,0]
	v_pk_mul_f32 v[28:29], v[38:39], v[34:35] op_sel_hi:[1,0]
	v_pk_mul_f32 v[26:27], v[148:149], v[26:27]
	v_pk_mul_f32 v[28:29], v[146:147], v[28:29]
	v_pk_fma_f32 v[26:27], v[60:61], v[26:27], v[144:145]
	v_pk_fma_f32 v[28:29], v[66:67], v[28:29], v[142:143]
	s_nop 0
	v_cvt_pk_bf16_f32 v29, v28, v29
	v_cvt_pk_bf16_f32 v26, v26, v27
	ds_read_b32 v28, v232 offset:192
	v_cndmask_b32_e32 v27, v26, v241, vcc
	v_cndmask_b32_e32 v26, v29, v241, vcc
	s_waitcnt lgkmcnt(0)
	v_pk_mul_f32 v[34:35], v[48:49], v[28:29] op_sel_hi:[1,0]
	v_pk_mul_f32 v[28:29], v[46:47], v[28:29] op_sel_hi:[1,0]
	v_pk_mul_f32 v[34:35], v[148:149], v[34:35]
	v_pk_mul_f32 v[28:29], v[146:147], v[28:29]
	v_pk_fma_f32 v[34:35], v[60:61], v[34:35], v[144:145]
	v_pk_fma_f32 v[28:29], v[66:67], v[28:29], v[142:143]
	s_nop 0
	v_cvt_pk_bf16_f32 v28, v28, v29
	v_cvt_pk_bf16_f32 v29, v34, v35
	ds_read_b32 v34, v232 offset:512
	v_cndmask_b32_e32 v29, v29, v241, vcc
	v_cndmask_b32_e32 v28, v28, v241, vcc
	s_nop 1
	v_permlane16_swap_b32_e32 v26, v28
	v_permlane16_swap_b32_e32 v27, v29
	global_store_dwordx4 v[92:93], v[26:29], off offset:256 sc1
	s_waitcnt lgkmcnt(0)
	s_nop 0
	v_pk_mul_f32 v[26:27], v[52:53], v[34:35] op_sel_hi:[1,0]
	v_pk_mul_f32 v[28:29], v[50:51], v[34:35] op_sel_hi:[1,0]
	v_pk_mul_f32 v[26:27], v[148:149], v[26:27]
	v_pk_mul_f32 v[28:29], v[146:147], v[28:29]
	v_pk_fma_f32 v[26:27], v[60:61], v[26:27], v[144:145]
	v_pk_fma_f32 v[28:29], v[66:67], v[28:29], v[142:143]
	s_nop 0
	v_cvt_pk_bf16_f32 v29, v28, v29
	v_cvt_pk_bf16_f32 v26, v26, v27
	ds_read_b32 v28, v232 offset:576
	v_cndmask_b32_e32 v27, v26, v241, vcc
	v_cndmask_b32_e32 v26, v29, v241, vcc
	s_waitcnt lgkmcnt(0)
	v_pk_mul_f32 v[34:35], v[56:57], v[28:29] op_sel_hi:[1,0]
	v_pk_mul_f32 v[28:29], v[54:55], v[28:29] op_sel_hi:[1,0]
	v_pk_mul_f32 v[34:35], v[148:149], v[34:35]
	v_pk_mul_f32 v[28:29], v[146:147], v[28:29]
	v_pk_fma_f32 v[34:35], v[60:61], v[34:35], v[144:145]
	v_pk_fma_f32 v[28:29], v[66:67], v[28:29], v[142:143]
	s_nop 0
	v_cvt_pk_bf16_f32 v28, v28, v29
	v_cvt_pk_bf16_f32 v29, v34, v35
	ds_read_b32 v34, v232 offset:640
	v_cndmask_b32_e32 v29, v29, v241, vcc
	v_cndmask_b32_e32 v28, v28, v241, vcc
	s_nop 1
	v_permlane16_swap_b32_e32 v26, v28
	v_permlane16_swap_b32_e32 v27, v29
	global_store_dwordx4 v[98:99], v[26:29], off offset:256 sc1
	s_waitcnt lgkmcnt(0)
	s_nop 0
	v_pk_mul_f32 v[26:27], v[64:65], v[34:35] op_sel_hi:[1,0]
	v_pk_mul_f32 v[28:29], v[62:63], v[34:35] op_sel_hi:[1,0]
	v_pk_mul_f32 v[26:27], v[148:149], v[26:27]
	v_pk_mul_f32 v[28:29], v[146:147], v[28:29]
	v_pk_fma_f32 v[26:27], v[60:61], v[26:27], v[144:145]
	v_pk_fma_f32 v[28:29], v[66:67], v[28:29], v[142:143]
	s_nop 0
	v_cvt_pk_bf16_f32 v29, v28, v29
	v_cvt_pk_bf16_f32 v26, v26, v27
	ds_read_b32 v28, v232 offset:704
	v_cndmask_b32_e32 v27, v26, v241, vcc
	v_cndmask_b32_e32 v26, v29, v241, vcc
	s_waitcnt lgkmcnt(0)
	v_pk_mul_f32 v[34:35], v[76:77], v[28:29] op_sel_hi:[1,0]
	v_pk_mul_f32 v[28:29], v[74:75], v[28:29] op_sel_hi:[1,0]
	v_pk_mul_f32 v[34:35], v[148:149], v[34:35]
	v_pk_mul_f32 v[28:29], v[146:147], v[28:29]
	v_pk_fma_f32 v[34:35], v[60:61], v[34:35], v[144:145]
	v_pk_fma_f32 v[28:29], v[66:67], v[28:29], v[142:143]
	s_nop 0
	v_cvt_pk_bf16_f32 v28, v28, v29
	v_cvt_pk_bf16_f32 v29, v34, v35
	v_pk_add_f32 v[34:35], v[138:139], 1.0 op_sel_hi:[1,0]
	v_cndmask_b32_e32 v29, v29, v241, vcc
	v_cndmask_b32_e32 v28, v28, v241, vcc
	s_nop 1
	v_permlane16_swap_b32_e32 v26, v28
	v_permlane16_swap_b32_e32 v27, v29
	global_store_dwordx4 v[100:101], v[26:29], off offset:256 sc1
	ds_read_b32 v26, v232
	s_waitcnt lgkmcnt(0)
	v_pk_mul_f32 v[4:5], v[4:5], v[26:27] op_sel_hi:[1,0]
	v_pk_mul_f32 v[2:3], v[2:3], v[26:27] op_sel_hi:[1,0]
	v_pk_add_f32 v[28:29], v[140:141], 1.0 op_sel_hi:[1,0]
	v_pk_mul_f32 v[4:5], v[132:133], v[4:5]
	v_pk_mul_f32 v[2:3], v[130:131], v[2:3]
	v_pk_fma_f32 v[4:5], v[28:29], v[4:5], v[136:137]
	v_pk_fma_f32 v[2:3], v[34:35], v[2:3], v[134:135]
	s_nop 0
	v_cvt_pk_bf16_f32 v2, v2, v3
	v_cvt_pk_bf16_f32 v3, v4, v5
	ds_read_b32 v4, v232 offset:64
	v_cndmask_b32_e32 v3, v3, v241, vcc
	v_cndmask_b32_e32 v2, v2, v241, vcc
	s_waitcnt lgkmcnt(0)
	v_pk_mul_f32 v[8:9], v[8:9], v[4:5] op_sel_hi:[1,0]
	v_pk_mul_f32 v[4:5], v[6:7], v[4:5] op_sel_hi:[1,0]
	v_pk_mul_f32 v[6:7], v[132:133], v[8:9]
	v_pk_mul_f32 v[4:5], v[130:131], v[4:5]
	v_pk_fma_f32 v[6:7], v[28:29], v[6:7], v[136:137]
	v_pk_fma_f32 v[4:5], v[34:35], v[4:5], v[134:135]
	s_nop 0
	v_cvt_pk_bf16_f32 v4, v4, v5
	v_cvt_pk_bf16_f32 v5, v6, v7
	ds_read_b32 v6, v232 offset:128
	v_cndmask_b32_e32 v5, v5, v241, vcc
	v_cndmask_b32_e32 v4, v4, v241, vcc
	s_nop 1
	v_permlane16_swap_b32_e32 v2, v4
	v_permlane16_swap_b32_e32 v3, v5
	global_store_dwordx4 v[90:91], v[2:5], off offset:288 sc1
	s_waitcnt lgkmcnt(0)
	s_nop 0
	v_pk_mul_f32 v[2:3], v[12:13], v[6:7] op_sel_hi:[1,0]
	v_pk_mul_f32 v[4:5], v[10:11], v[6:7] op_sel_hi:[1,0]
	v_pk_mul_f32 v[2:3], v[132:133], v[2:3]
	v_pk_mul_f32 v[4:5], v[130:131], v[4:5]
	v_pk_fma_f32 v[2:3], v[28:29], v[2:3], v[136:137]
	v_pk_fma_f32 v[4:5], v[34:35], v[4:5], v[134:135]
	s_nop 0
	v_cvt_pk_bf16_f32 v5, v4, v5
	v_cvt_pk_bf16_f32 v2, v2, v3
	ds_read_b32 v4, v232 offset:192
	v_cndmask_b32_e32 v3, v2, v241, vcc
	v_cndmask_b32_e32 v2, v5, v241, vcc
	s_waitcnt lgkmcnt(0)
	v_pk_mul_f32 v[6:7], v[16:17], v[4:5] op_sel_hi:[1,0]
	v_pk_mul_f32 v[4:5], v[14:15], v[4:5] op_sel_hi:[1,0]
	v_pk_mul_f32 v[6:7], v[132:133], v[6:7]
	v_pk_mul_f32 v[4:5], v[130:131], v[4:5]
	v_pk_fma_f32 v[6:7], v[28:29], v[6:7], v[136:137]
	v_pk_fma_f32 v[4:5], v[34:35], v[4:5], v[134:135]
	s_nop 0
	v_cvt_pk_bf16_f32 v4, v4, v5
	v_cvt_pk_bf16_f32 v5, v6, v7
	ds_read_b32 v6, v232 offset:512
	v_cndmask_b32_e32 v5, v5, v241, vcc
	v_cndmask_b32_e32 v4, v4, v241, vcc
	s_nop 1
	v_permlane16_swap_b32_e32 v2, v4
	v_permlane16_swap_b32_e32 v3, v5
	global_store_dwordx4 v[92:93], v[2:5], off offset:288 sc1
	s_waitcnt lgkmcnt(0)
	s_nop 0
	v_pk_mul_f32 v[2:3], v[20:21], v[6:7] op_sel_hi:[1,0]
	v_pk_mul_f32 v[4:5], v[18:19], v[6:7] op_sel_hi:[1,0]
	v_pk_mul_f32 v[2:3], v[132:133], v[2:3]
	v_pk_mul_f32 v[4:5], v[130:131], v[4:5]
	v_pk_fma_f32 v[2:3], v[28:29], v[2:3], v[136:137]
	v_pk_fma_f32 v[4:5], v[34:35], v[4:5], v[134:135]
	s_nop 0
	v_cvt_pk_bf16_f32 v5, v4, v5
	v_cvt_pk_bf16_f32 v2, v2, v3
	ds_read_b32 v4, v232 offset:576
	v_cndmask_b32_e32 v3, v2, v241, vcc
	v_cndmask_b32_e32 v2, v5, v241, vcc
	s_waitcnt lgkmcnt(0)
	v_pk_mul_f32 v[6:7], v[24:25], v[4:5] op_sel_hi:[1,0]
	v_pk_mul_f32 v[4:5], v[22:23], v[4:5] op_sel_hi:[1,0]
	v_pk_mul_f32 v[6:7], v[132:133], v[6:7]
	v_pk_mul_f32 v[4:5], v[130:131], v[4:5]
	v_pk_fma_f32 v[6:7], v[28:29], v[6:7], v[136:137]
	v_pk_fma_f32 v[4:5], v[34:35], v[4:5], v[134:135]
	s_nop 0
	v_cvt_pk_bf16_f32 v4, v4, v5
	v_cvt_pk_bf16_f32 v5, v6, v7
	ds_read_b32 v6, v232 offset:640
	v_cndmask_b32_e32 v5, v5, v241, vcc
	v_cndmask_b32_e32 v4, v4, v241, vcc
	s_nop 1
	v_permlane16_swap_b32_e32 v2, v4
	v_permlane16_swap_b32_e32 v3, v5
	global_store_dwordx4 v[98:99], v[2:5], off offset:288 sc1
	s_waitcnt lgkmcnt(0)
	s_nop 0
	v_pk_mul_f32 v[2:3], v[32:33], v[6:7] op_sel_hi:[1,0]
	v_pk_mul_f32 v[4:5], v[30:31], v[6:7] op_sel_hi:[1,0]
	v_pk_mul_f32 v[2:3], v[132:133], v[2:3]
	v_pk_mul_f32 v[4:5], v[130:131], v[4:5]
	v_pk_fma_f32 v[2:3], v[28:29], v[2:3], v[136:137]
	v_pk_fma_f32 v[4:5], v[34:35], v[4:5], v[134:135]
	s_nop 0
	v_cvt_pk_bf16_f32 v5, v4, v5
	v_cvt_pk_bf16_f32 v2, v2, v3
	ds_read_b32 v4, v232 offset:704
	v_cndmask_b32_e32 v3, v2, v241, vcc
	v_cndmask_b32_e32 v2, v5, v241, vcc
	s_waitcnt lgkmcnt(0)
	v_pk_mul_f32 v[6:7], v[44:45], v[4:5] op_sel_hi:[1,0]
	v_pk_mul_f32 v[4:5], v[42:43], v[4:5] op_sel_hi:[1,0]
	v_pk_mul_f32 v[6:7], v[132:133], v[6:7]
	v_pk_mul_f32 v[4:5], v[130:131], v[4:5]
	v_pk_fma_f32 v[6:7], v[28:29], v[6:7], v[136:137]
	v_pk_fma_f32 v[4:5], v[34:35], v[4:5], v[134:135]
	s_nop 0
	v_cvt_pk_bf16_f32 v4, v4, v5
	v_cvt_pk_bf16_f32 v5, v6, v7
	s_nop 0
	v_cndmask_b32_e32 v5, v5, v241, vcc
	v_cndmask_b32_e32 v4, v4, v241, vcc
	s_nop 1
	v_permlane16_swap_b32_e32 v2, v4
	v_permlane16_swap_b32_e32 v3, v5
	global_store_dwordx4 v[100:101], v[2:5], off offset:288
	s_andn2_b64 vcc, exec, s[56:57]
	s_cbranch_vccnz .LBB0_670
	s_andn2_b64 vcc, exec, s[42:43]
	s_cbranch_vccnz .LBB0_669
	s_barrier
	s_branch .LBB0_669

.LBB0_791:
	v_pk_mul_f32 v[158:159], v[128:129], s[10:11] op_sel_hi:[1,0]
	v_pk_mul_f32 v[160:161], v[126:127], s[10:11] op_sel_hi:[1,0]
	v_exp_f32_e32 v158, v158
	v_exp_f32_e32 v160, v160
	v_exp_f32_e32 v159, v159
	v_exp_f32_e32 v161, v161
	v_pk_mul_f32 v[124:125], v[128:129], v[124:125]
	v_pk_mul_f32 v[122:123], v[126:127], v[122:123]
	v_pk_add_f32 v[158:159], v[158:159], 1.0 op_sel_hi:[1,0]
	v_pk_add_f32 v[160:161], v[160:161], 1.0 op_sel_hi:[1,0]
	v_rcp_f32_e32 v158, v158
	v_rcp_f32_e32 v160, v160
	v_rcp_f32_e32 v159, v159
	v_rcp_f32_e32 v161, v161
	v_pk_mul_f32 v[126:127], v[120:121], s[10:11] op_sel_hi:[1,0]
	v_pk_mul_f32 v[128:129], v[118:119], s[10:11] op_sel_hi:[1,0]
	v_exp_f32_e32 v126, v126
	v_exp_f32_e32 v128, v128
	v_exp_f32_e32 v127, v127
	v_exp_f32_e32 v129, v129
	v_pk_mul_f32 v[124:125], v[124:125], v[158:159]
	v_pk_mul_f32 v[122:123], v[122:123], v[160:161]
	v_pk_mul_f32 v[116:117], v[120:121], v[116:117]
	v_cvt_pk_bf16_f32 v122, v122, v123
	v_cvt_pk_bf16_f32 v123, v124, v125
	v_pk_add_f32 v[124:125], v[126:127], 1.0 op_sel_hi:[1,0]
	v_pk_add_f32 v[126:127], v[128:129], 1.0 op_sel_hi:[1,0]
	v_rcp_f32_e32 v124, v124
	v_rcp_f32_e32 v126, v126
	v_rcp_f32_e32 v125, v125
	v_rcp_f32_e32 v127, v127
	v_pk_mul_f32 v[114:115], v[118:119], v[114:115]
	v_pk_mul_f32 v[108:109], v[112:113], v[108:109]
	v_pk_mul_f32 v[116:117], v[116:117], v[124:125]
	v_pk_mul_f32 v[114:115], v[114:115], v[126:127]
	v_pk_mul_f32 v[106:107], v[110:111], v[106:107]
	v_cvt_pk_bf16_f32 v124, v114, v115
	v_cvt_pk_bf16_f32 v125, v116, v117
	v_pk_mul_f32 v[114:115], v[112:113], s[10:11] op_sel_hi:[1,0]
	v_pk_mul_f32 v[116:117], v[110:111], s[10:11] op_sel_hi:[1,0]
	v_exp_f32_e32 v114, v114
	v_exp_f32_e32 v116, v116
	v_exp_f32_e32 v117, v117
	v_exp_f32_e32 v115, v115
	v_pk_mul_f32 v[110:111], v[104:105], s[10:11] op_sel_hi:[1,0]
	v_pk_mul_f32 v[112:113], v[102:103], s[10:11] op_sel_hi:[1,0]
	v_pk_add_f32 v[116:117], v[116:117], 1.0 op_sel_hi:[1,0]
	v_pk_add_f32 v[114:115], v[114:115], 1.0 op_sel_hi:[1,0]
	v_rcp_f32_e32 v116, v116
	v_rcp_f32_e32 v114, v114
	v_rcp_f32_e32 v115, v115
	v_rcp_f32_e32 v117, v117
	s_lshl_b32 s26, s49, 7
	v_exp_f32_e32 v112, v112
	v_exp_f32_e32 v110, v110
	v_exp_f32_e32 v111, v111
	v_exp_f32_e32 v113, v113
	s_ashr_i32 s27, s26, 31
	v_lshl_add_u64 v[148:149], s[26:27], 1, v[138:139]
	v_lshl_add_u32 v156, s24, 8, v152
	v_mad_i64_i32 v[162:163], s[26:27], v156, s48, v[148:149]
	v_permlane16_swap_b32_e32 v122, v124
	v_permlane16_swap_b32_e32 v123, v125
	v_pk_mul_f32 v[108:109], v[108:109], v[114:115]
	v_pk_mul_f32 v[106:107], v[106:107], v[116:117]
	global_store_dwordx4 v[162:163], v[122:125], off sc1
	v_cvt_pk_bf16_f32 v106, v106, v107
	v_cvt_pk_bf16_f32 v107, v108, v109
	v_pk_add_f32 v[108:109], v[110:111], 1.0 op_sel_hi:[1,0]
	v_pk_add_f32 v[110:111], v[112:113], 1.0 op_sel_hi:[1,0]
	v_rcp_f32_e32 v108, v108
	v_rcp_f32_e32 v110, v110
	v_rcp_f32_e32 v109, v109
	v_rcp_f32_e32 v111, v111
	v_pk_mul_f32 v[100:101], v[104:105], v[100:101]
	v_pk_mul_f32 v[98:99], v[102:103], v[98:99]
	v_pk_mul_f32 v[100:101], v[100:101], v[108:109]
	v_pk_mul_f32 v[98:99], v[98:99], v[110:111]
	v_pk_mul_f32 v[92:93], v[96:97], v[92:93]
	v_cvt_pk_bf16_f32 v108, v98, v99
	v_cvt_pk_bf16_f32 v109, v100, v101
	v_pk_mul_f32 v[98:99], v[96:97], s[10:11] op_sel_hi:[1,0]
	v_pk_mul_f32 v[100:101], v[94:95], s[10:11] op_sel_hi:[1,0]
	v_exp_f32_e32 v98, v98
	v_exp_f32_e32 v100, v100
	v_exp_f32_e32 v99, v99
	v_exp_f32_e32 v101, v101
	v_pk_mul_f32 v[90:91], v[94:95], v[90:91]
	v_pk_mul_f32 v[94:95], v[88:89], s[10:11] op_sel_hi:[1,0]
	v_pk_add_f32 v[98:99], v[98:99], 1.0 op_sel_hi:[1,0]
	v_pk_add_f32 v[100:101], v[100:101], 1.0 op_sel_hi:[1,0]
	v_rcp_f32_e32 v98, v98
	v_rcp_f32_e32 v100, v100
	v_rcp_f32_e32 v99, v99
	v_rcp_f32_e32 v101, v101
	v_pk_mul_f32 v[96:97], v[86:87], s[10:11] op_sel_hi:[1,0]
	v_exp_f32_e32 v94, v94
	v_exp_f32_e32 v96, v96
	v_exp_f32_e32 v95, v95
	v_exp_f32_e32 v97, v97
	v_permlane16_swap_b32_e32 v106, v108
	v_permlane16_swap_b32_e32 v107, v109
	v_pk_mul_f32 v[92:93], v[92:93], v[98:99]
	v_pk_mul_f32 v[90:91], v[90:91], v[100:101]
	global_store_dwordx4 v[162:163], v[106:109], off offset:128 sc1
	v_cvt_pk_bf16_f32 v90, v90, v91
	v_cvt_pk_bf16_f32 v91, v92, v93
	v_pk_add_f32 v[92:93], v[94:95], 1.0 op_sel_hi:[1,0]
	v_pk_add_f32 v[94:95], v[96:97], 1.0 op_sel_hi:[1,0]
	v_rcp_f32_e32 v92, v92
	v_rcp_f32_e32 v94, v94
	v_rcp_f32_e32 v93, v93
	v_rcp_f32_e32 v95, v95
	v_pk_mul_f32 v[84:85], v[88:89], v[84:85]
	v_pk_mul_f32 v[82:83], v[86:87], v[82:83]
	v_pk_mul_f32 v[84:85], v[84:85], v[92:93]
	v_pk_mul_f32 v[82:83], v[82:83], v[94:95]
	v_pk_mul_f32 v[76:77], v[80:81], v[76:77]
	v_cvt_pk_bf16_f32 v92, v82, v83
	v_cvt_pk_bf16_f32 v93, v84, v85
	v_pk_mul_f32 v[82:83], v[80:81], s[10:11] op_sel_hi:[1,0]
	v_pk_mul_f32 v[84:85], v[78:79], s[10:11] op_sel_hi:[1,0]
	v_exp_f32_e32 v82, v82
	v_exp_f32_e32 v84, v84
	v_exp_f32_e32 v85, v85
	v_exp_f32_e32 v83, v83
	v_pk_mul_f32 v[74:75], v[78:79], v[74:75]
	v_pk_mul_f32 v[78:79], v[72:73], s[10:11] op_sel_hi:[1,0]
	v_pk_add_f32 v[84:85], v[84:85], 1.0 op_sel_hi:[1,0]
	v_pk_add_f32 v[82:83], v[82:83], 1.0 op_sel_hi:[1,0]
	v_rcp_f32_e32 v84, v84
	v_rcp_f32_e32 v82, v82
	v_rcp_f32_e32 v83, v83
	v_rcp_f32_e32 v85, v85
	v_pk_mul_f32 v[80:81], v[70:71], s[10:11] op_sel_hi:[1,0]
	v_exp_f32_e32 v78, v78
	v_exp_f32_e32 v80, v80
	v_exp_f32_e32 v79, v79
	v_exp_f32_e32 v81, v81
	v_or_b32_e32 v102, 32, v156
	v_mad_i64_i32 v[102:103], s[26:27], v102, s48, v[148:149]
	v_permlane16_swap_b32_e32 v90, v92
	v_permlane16_swap_b32_e32 v91, v93
	v_pk_mul_f32 v[76:77], v[76:77], v[82:83]
	v_pk_mul_f32 v[74:75], v[74:75], v[84:85]
	global_store_dwordx4 v[102:103], v[90:93], off sc1
	v_cvt_pk_bf16_f32 v74, v74, v75
	v_cvt_pk_bf16_f32 v75, v76, v77
	v_pk_add_f32 v[76:77], v[78:79], 1.0 op_sel_hi:[1,0]
	v_pk_add_f32 v[78:79], v[80:81], 1.0 op_sel_hi:[1,0]
	v_rcp_f32_e32 v76, v76
	v_rcp_f32_e32 v78, v78
	v_rcp_f32_e32 v77, v77
	v_rcp_f32_e32 v79, v79
	v_pk_mul_f32 v[68:69], v[72:73], v[68:69]
	v_pk_mul_f32 v[66:67], v[70:71], v[66:67]
	v_pk_mul_f32 v[68:69], v[68:69], v[76:77]
	v_pk_mul_f32 v[66:67], v[66:67], v[78:79]
	v_pk_mul_f32 v[60:61], v[64:65], v[60:61]
	v_cvt_pk_bf16_f32 v76, v66, v67
	v_cvt_pk_bf16_f32 v77, v68, v69
	v_pk_mul_f32 v[66:67], v[64:65], s[10:11] op_sel_hi:[1,0]
	v_pk_mul_f32 v[68:69], v[62:63], s[10:11] op_sel_hi:[1,0]
	v_exp_f32_e32 v66, v66
	v_exp_f32_e32 v68, v68
	v_exp_f32_e32 v67, v67
	v_exp_f32_e32 v69, v69
	v_pk_mul_f32 v[58:59], v[62:63], v[58:59]
	v_pk_mul_f32 v[62:63], v[56:57], s[10:11] op_sel_hi:[1,0]
	v_pk_add_f32 v[66:67], v[66:67], 1.0 op_sel_hi:[1,0]
	v_pk_add_f32 v[68:69], v[68:69], 1.0 op_sel_hi:[1,0]
	v_rcp_f32_e32 v66, v66
	v_rcp_f32_e32 v68, v68
	v_rcp_f32_e32 v67, v67
	v_rcp_f32_e32 v69, v69
	v_pk_mul_f32 v[64:65], v[54:55], s[10:11] op_sel_hi:[1,0]
	v_exp_f32_e32 v62, v62
	v_exp_f32_e32 v64, v64
	v_exp_f32_e32 v63, v63
	v_exp_f32_e32 v65, v65
	v_permlane16_swap_b32_e32 v74, v76
	v_permlane16_swap_b32_e32 v75, v77
	v_pk_mul_f32 v[60:61], v[60:61], v[66:67]
	v_pk_mul_f32 v[58:59], v[58:59], v[68:69]
	global_store_dwordx4 v[102:103], v[74:77], off offset:128 sc1
	v_cvt_pk_bf16_f32 v58, v58, v59
	v_cvt_pk_bf16_f32 v59, v60, v61
	v_pk_add_f32 v[60:61], v[62:63], 1.0 op_sel_hi:[1,0]
	v_pk_add_f32 v[62:63], v[64:65], 1.0 op_sel_hi:[1,0]
	v_rcp_f32_e32 v60, v60
	v_rcp_f32_e32 v62, v62
	v_rcp_f32_e32 v61, v61
	v_rcp_f32_e32 v63, v63
	v_pk_mul_f32 v[52:53], v[56:57], v[52:53]
	v_pk_mul_f32 v[50:51], v[54:55], v[50:51]
	v_pk_mul_f32 v[52:53], v[52:53], v[60:61]
	v_pk_mul_f32 v[50:51], v[50:51], v[62:63]
	v_pk_mul_f32 v[44:45], v[48:49], v[44:45]
	v_cvt_pk_bf16_f32 v60, v50, v51
	v_cvt_pk_bf16_f32 v61, v52, v53
	v_pk_mul_f32 v[50:51], v[48:49], s[10:11] op_sel_hi:[1,0]
	v_pk_mul_f32 v[52:53], v[46:47], s[10:11] op_sel_hi:[1,0]
	v_exp_f32_e32 v50, v50
	v_exp_f32_e32 v52, v52
	v_exp_f32_e32 v53, v53
	v_exp_f32_e32 v51, v51
	v_pk_mul_f32 v[42:43], v[46:47], v[42:43]
	v_pk_mul_f32 v[46:47], v[40:41], s[10:11] op_sel_hi:[1,0]
	v_pk_add_f32 v[52:53], v[52:53], 1.0 op_sel_hi:[1,0]
	v_pk_add_f32 v[50:51], v[50:51], 1.0 op_sel_hi:[1,0]
	v_rcp_f32_e32 v52, v52
	v_rcp_f32_e32 v50, v50
	v_rcp_f32_e32 v51, v51
	v_rcp_f32_e32 v53, v53
	v_pk_mul_f32 v[48:49], v[38:39], s[10:11] op_sel_hi:[1,0]
	v_exp_f32_e32 v46, v46
	v_exp_f32_e32 v48, v48
	v_exp_f32_e32 v47, v47
	v_exp_f32_e32 v49, v49
	v_add_u32_e32 v70, 0x80, v156
	v_mad_i64_i32 v[70:71], s[26:27], v70, s48, v[148:149]
	v_permlane16_swap_b32_e32 v58, v60
	v_permlane16_swap_b32_e32 v59, v61
	v_pk_mul_f32 v[44:45], v[44:45], v[50:51]
	v_pk_mul_f32 v[42:43], v[42:43], v[52:53]
	global_store_dwordx4 v[70:71], v[58:61], off sc1
	v_cvt_pk_bf16_f32 v42, v42, v43
	v_cvt_pk_bf16_f32 v43, v44, v45
	v_pk_add_f32 v[44:45], v[46:47], 1.0 op_sel_hi:[1,0]
	v_pk_add_f32 v[46:47], v[48:49], 1.0 op_sel_hi:[1,0]
	v_rcp_f32_e32 v44, v44
	v_rcp_f32_e32 v46, v46
	v_rcp_f32_e32 v45, v45
	v_rcp_f32_e32 v47, v47
	v_pk_mul_f32 v[36:37], v[40:41], v[36:37]
	v_pk_mul_f32 v[34:35], v[38:39], v[34:35]
	v_pk_mul_f32 v[36:37], v[36:37], v[44:45]
	v_pk_mul_f32 v[34:35], v[34:35], v[46:47]
	v_pk_mul_f32 v[28:29], v[32:33], v[28:29]
	v_cvt_pk_bf16_f32 v44, v34, v35
	v_cvt_pk_bf16_f32 v45, v36, v37
	v_pk_mul_f32 v[34:35], v[32:33], s[10:11] op_sel_hi:[1,0]
	v_pk_mul_f32 v[36:37], v[30:31], s[10:11] op_sel_hi:[1,0]
	v_exp_f32_e32 v34, v34
	v_exp_f32_e32 v36, v36
	v_exp_f32_e32 v35, v35
	v_exp_f32_e32 v37, v37
	v_pk_mul_f32 v[26:27], v[30:31], v[26:27]
	v_pk_mul_f32 v[30:31], v[24:25], s[10:11] op_sel_hi:[1,0]
	v_pk_add_f32 v[34:35], v[34:35], 1.0 op_sel_hi:[1,0]
	v_pk_add_f32 v[36:37], v[36:37], 1.0 op_sel_hi:[1,0]
	v_rcp_f32_e32 v34, v34
	v_rcp_f32_e32 v36, v36
	v_rcp_f32_e32 v35, v35
	v_rcp_f32_e32 v37, v37
	v_pk_mul_f32 v[32:33], v[22:23], s[10:11] op_sel_hi:[1,0]
	v_exp_f32_e32 v30, v30
	v_exp_f32_e32 v32, v32
	v_exp_f32_e32 v31, v31
	v_exp_f32_e32 v33, v33
	v_permlane16_swap_b32_e32 v42, v44
	v_permlane16_swap_b32_e32 v43, v45
	v_pk_mul_f32 v[28:29], v[28:29], v[34:35]
	v_pk_mul_f32 v[26:27], v[26:27], v[36:37]
	global_store_dwordx4 v[70:71], v[42:45], off offset:128 sc1
	v_cvt_pk_bf16_f32 v26, v26, v27
	v_cvt_pk_bf16_f32 v27, v28, v29
	v_pk_add_f32 v[28:29], v[30:31], 1.0 op_sel_hi:[1,0]
	v_pk_add_f32 v[30:31], v[32:33], 1.0 op_sel_hi:[1,0]
	v_rcp_f32_e32 v28, v28
	v_rcp_f32_e32 v30, v30
	v_rcp_f32_e32 v29, v29
	v_rcp_f32_e32 v31, v31
	v_pk_mul_f32 v[20:21], v[24:25], v[20:21]
	v_pk_mul_f32 v[18:19], v[22:23], v[18:19]
	v_pk_mul_f32 v[20:21], v[20:21], v[28:29]
	v_pk_mul_f32 v[18:19], v[18:19], v[30:31]
	v_pk_mul_f32 v[12:13], v[16:17], v[12:13]
	v_cvt_pk_bf16_f32 v28, v18, v19
	v_cvt_pk_bf16_f32 v29, v20, v21
	v_pk_mul_f32 v[18:19], v[16:17], s[10:11] op_sel_hi:[1,0]
	v_pk_mul_f32 v[20:21], v[14:15], s[10:11] op_sel_hi:[1,0]
	v_exp_f32_e32 v18, v18
	v_exp_f32_e32 v20, v20
	v_exp_f32_e32 v21, v21
	v_exp_f32_e32 v19, v19
	v_pk_mul_f32 v[10:11], v[14:15], v[10:11]
	v_pk_mul_f32 v[14:15], v[8:9], s[10:11] op_sel_hi:[1,0]
	v_pk_add_f32 v[20:21], v[20:21], 1.0 op_sel_hi:[1,0]
	v_pk_add_f32 v[18:19], v[18:19], 1.0 op_sel_hi:[1,0]
	v_rcp_f32_e32 v20, v20
	v_rcp_f32_e32 v18, v18
	v_rcp_f32_e32 v19, v19
	v_rcp_f32_e32 v21, v21
	v_pk_mul_f32 v[16:17], v[6:7], s[10:11] op_sel_hi:[1,0]
	v_exp_f32_e32 v14, v14
	v_exp_f32_e32 v16, v16
	v_exp_f32_e32 v15, v15
	v_exp_f32_e32 v17, v17
	v_add_u32_e32 v38, 0xa0, v156
	v_mad_i64_i32 v[38:39], s[26:27], v38, s48, v[148:149]
	v_permlane16_swap_b32_e32 v26, v28
	v_permlane16_swap_b32_e32 v27, v29
	v_pk_mul_f32 v[12:13], v[12:13], v[18:19]
	v_pk_mul_f32 v[10:11], v[10:11], v[20:21]
	global_store_dwordx4 v[38:39], v[26:29], off sc1
	v_cvt_pk_bf16_f32 v10, v10, v11
	v_cvt_pk_bf16_f32 v11, v12, v13
	v_pk_add_f32 v[12:13], v[14:15], 1.0 op_sel_hi:[1,0]
	v_pk_add_f32 v[14:15], v[16:17], 1.0 op_sel_hi:[1,0]
	v_rcp_f32_e32 v12, v12
	v_rcp_f32_e32 v14, v14
	v_rcp_f32_e32 v13, v13
	v_rcp_f32_e32 v15, v15
	v_pk_mul_f32 v[4:5], v[8:9], v[4:5]
	v_pk_mul_f32 v[2:3], v[6:7], v[2:3]
	v_pk_mul_f32 v[4:5], v[4:5], v[12:13]
	v_pk_mul_f32 v[2:3], v[2:3], v[14:15]
	s_andn2_b64 vcc, exec, s[2:3]
	v_cvt_pk_bf16_f32 v12, v2, v3
	v_cvt_pk_bf16_f32 v13, v4, v5
	s_mov_b64 s[2:3], -1
	v_permlane16_swap_b32_e32 v10, v12
	v_permlane16_swap_b32_e32 v11, v13
	global_store_dwordx4 v[38:39], v[10:13], off offset:128 sc1
	s_cbranch_vccnz .LBB0_784
	s_andn2_b64 vcc, exec, s[4:5]
	s_cbranch_vccnz .LBB0_783
	s_barrier
	s_branch .LBB0_783
